# mixer A combine loop unrolled by hand with two register sets: each pass's 28 loads are issued one pass ahead (no exposed round trip per pass)
# speedup vs baseline: 1.0025x; 1.0025x over previous
; __device__ __forceinline__ void attnA_unit(LAS unsigned char* lds, const Args& A, int unit) {
;     ...
;     for (int it0 = 0; it0 < 16; it0 += 4) {
;         float ls2[4][3]; u32x4 og[4][3], zv[4];
; #pragma unroll
;         for (int q = 0; q < 4; ++q) {
;             const int e = (it0 + q) * 512 + tid, tl = e >> 3, ch = e & 7, s = c * 1024 + tl;
; #pragma unroll
;             for (int g = 0; g < 3; ++g) { const int lg = 2 * g, p = ((s & ((1 << lg) - 1)) << (13 - lg)) | (s >> lg);
;                 ls2[q][g] = LSE[(size_t)((g * 4 + b) * 8 + h) * 8192 + p];
;                 og[q][g] = *(const u32x4*)((const bf16*)(A.ws + WS_QA) + ((size_t)((b * 3 + g) * 8 + h) * 8192 + p) * 64 + ch * 8); }
;             zv[q] = *(const u32x4*)(SAZ + (size_t)(b * 8192 + s) * 512 + h * 64 + ch * 8);
;         }
.LBB0_309:
	v_add_u32_e32 v16, 0x200, v145
	v_add_u32_e32 v32, 0x400, v145
	v_add_u32_e32 v48, 0x600, v145
	v_ashrrev_i32_e32 v74, 3, v145
	v_ashrrev_i32_e32 v76, 3, v16
	s_waitcnt vmcnt(8)
	v_ashrrev_i32_e32 v92, 3, v32
	v_ashrrev_i32_e32 v96, 3, v48
	v_add_u32_e32 v12, s10, v74
	v_add_u32_e32 v28, s10, v76
	v_add_u32_e32 v44, s10, v92
	v_add_u32_e32 v60, s10, v96
	v_lshlrev_b32_e32 v4, 11, v74
	v_ashrrev_i32_e32 v5, 2, v12
	v_lshlrev_b32_e32 v20, 11, v76
	v_ashrrev_i32_e32 v21, 2, v28
	v_lshlrev_b32_e32 v24, 9, v76
	v_ashrrev_i32_e32 v25, 4, v28
	v_lshlrev_b32_e32 v36, 11, v92
	v_ashrrev_i32_e32 v37, 2, v44
	v_lshlrev_b32_e32 v40, 9, v92
	v_ashrrev_i32_e32 v41, 4, v44
	v_lshlrev_b32_e32 v52, 11, v96
	v_ashrrev_i32_e32 v53, 2, v60
	v_lshlrev_b32_e32 v56, 9, v96
	v_ashrrev_i32_e32 v57, 4, v60
	v_and_or_b32 v4, v4, s89, v5
	v_lshlrev_b32_e32 v8, 9, v74
	v_ashrrev_i32_e32 v9, 4, v12
	v_and_or_b32 v20, v20, s89, v21
	v_and_or_b32 v24, v24, s50, v25
	v_and_or_b32 v36, v36, s89, v37
	v_and_or_b32 v40, v40, s50, v41
	v_and_or_b32 v52, v52, s89, v53
	v_and_or_b32 v56, v56, s50, v57
	v_ashrrev_i32_e32 v5, 31, v4
	v_and_or_b32 v8, v8, s50, v9
	v_ashrrev_i32_e32 v21, 31, v20
	v_ashrrev_i32_e32 v25, 31, v24
	v_ashrrev_i32_e32 v37, 31, v36
	v_ashrrev_i32_e32 v41, 31, v40
	v_ashrrev_i32_e32 v53, 31, v52
	v_ashrrev_i32_e32 v57, 31, v56
	v_ashrrev_i32_e32 v13, 31, v12
	v_lshl_add_u64 v[6:7], v[4:5], 2, s[6:7]
	v_lshlrev_b64 v[4:5], 7, v[4:5]
	v_ashrrev_i32_e32 v9, 31, v8
	v_ashrrev_i32_e32 v29, 31, v28
	v_lshl_add_u64 v[22:23], v[20:21], 2, s[6:7]
	v_lshlrev_b64 v[20:21], 7, v[20:21]
	v_lshl_add_u64 v[26:27], v[24:25], 2, s[8:9]
	v_lshlrev_b64 v[24:25], 7, v[24:25]
	v_ashrrev_i32_e32 v45, 31, v44
	v_lshl_add_u64 v[38:39], v[36:37], 2, s[6:7]
	v_lshlrev_b64 v[36:37], 7, v[36:37]
	v_lshl_add_u64 v[42:43], v[40:41], 2, s[8:9]
	v_lshlrev_b64 v[40:41], 7, v[40:41]
	v_ashrrev_i32_e32 v61, 31, v60
	v_lshl_add_u64 v[54:55], v[52:53], 2, s[6:7]
	v_lshlrev_b64 v[52:53], 7, v[52:53]
	v_lshl_add_u64 v[58:59], v[56:57], 2, s[8:9]
	v_lshlrev_b64 v[56:57], 7, v[56:57]
	v_lshl_add_u64 v[0:1], v[12:13], 2, s[4:5]
	v_lshl_add_u64 v[4:5], v[70:71], 0, v[4:5]
	v_lshl_add_u64 v[10:11], v[8:9], 2, s[8:9]
	v_lshl_add_u64 v[16:17], v[28:29], 2, s[4:5]
	v_lshl_add_u64 v[20:21], v[70:71], 0, v[20:21]
	v_lshl_add_u64 v[24:25], v[72:73], 0, v[24:25]
	v_lshl_add_u64 v[32:33], v[44:45], 2, s[4:5]
	v_lshl_add_u64 v[36:37], v[70:71], 0, v[36:37]
	v_lshl_add_u64 v[40:41], v[72:73], 0, v[40:41]
	v_lshl_add_u64 v[48:49], v[60:61], 2, s[4:5]
	v_lshl_add_u64 v[52:53], v[70:71], 0, v[52:53]
	v_lshl_add_u64 v[56:57], v[72:73], 0, v[56:57]
	global_load_dword v75, v[0:1], off
	global_load_dword v80, v[10:11], off
	global_load_dword v77, v[6:7], off
	global_load_dword v83, v[16:17], off
	global_load_dword v90, v[22:23], off
	global_load_dword v93, v[32:33], off
	global_load_dword v91, v[26:27], off
	global_load_dword v94, v[38:39], off
	global_load_dword v97, v[48:49], off
	global_load_dword v95, v[42:43], off
	global_load_dword v98, v[54:55], off
	global_load_dword v99, v[58:59], off
	v_lshlrev_b64 v[8:9], 7, v[8:9]
	global_load_dwordx4 v[56:59], v[56:57], off
	v_lshl_add_u64 v[8:9], v[72:73], 0, v[8:9]
	global_load_dwordx4 v[52:55], v[52:53], off
	v_lshlrev_b64 v[32:33], 7, v[44:45]
	global_load_dwordx4 v[40:43], v[40:41], off
	v_lshl_add_u64 v[32:33], v[68:69], 0, v[32:33]
	global_load_dwordx4 v[36:39], v[36:37], off
	v_add_u32_e32 v44, s11, v44
	global_load_dwordx4 v[24:27], v[24:25], off
	v_ashrrev_i32_e32 v45, 31, v44
	global_load_dwordx4 v[20:23], v[20:21], off
	v_lshlrev_b64 v[16:17], 7, v[28:29]
	global_load_dwordx4 v[4:7], v[4:5], off
	v_lshlrev_b64 v[0:1], 7, v[12:13]
	v_lshl_add_u64 v[0:1], v[68:69], 0, v[0:1]
	v_add_u32_e32 v12, s11, v12
	global_load_dwordx4 v[0:3], v[0:1], off
	v_ashrrev_i32_e32 v13, 31, v12
	v_lshlrev_b64 v[12:13], 10, v[12:13]
	global_load_dwordx4 v[8:11], v[8:9], off
	v_lshl_add_u64 v[12:13], v[64:65], 0, v[12:13]
	global_load_dwordx4 v[12:15], v[12:13], off
	v_lshl_add_u64 v[16:17], v[68:69], 0, v[16:17]
	global_load_dwordx4 v[16:19], v[16:17], off
	v_add_u32_e32 v28, s11, v28
	v_ashrrev_i32_e32 v29, 31, v28
	v_lshlrev_b64 v[28:29], 10, v[28:29]
	v_lshl_add_u64 v[28:29], v[64:65], 0, v[28:29]
	global_load_dwordx4 v[28:31], v[28:29], off
	v_lshlrev_b64 v[44:45], 10, v[44:45]
	global_load_dwordx4 v[32:35], v[32:33], off
	v_lshl_add_u64 v[44:45], v[64:65], 0, v[44:45]
	global_load_dwordx4 v[44:47], v[44:45], off
	v_lshlrev_b64 v[48:49], 7, v[60:61]
	v_add_u32_e32 v60, s11, v60
	v_ashrrev_i32_e32 v61, 31, v60
	v_lshlrev_b64 v[60:61], 10, v[60:61]
	v_lshl_add_u64 v[48:49], v[68:69], 0, v[48:49]
	v_lshl_add_u64 v[60:61], v[64:65], 0, v[60:61]
	global_load_dwordx4 v[48:51], v[48:49], off
	global_load_dwordx4 v[60:63], v[60:61], off
	v_add_u32_e32 v145, 0x800, v145
	v_add_u32_e32 v116, 0x200, v145
	v_add_u32_e32 v132, 0x400, v145
	v_add_u32_e32 v194, 0x600, v145
	v_ashrrev_i32_e32 v146, 3, v145
	v_ashrrev_i32_e32 v148, 3, v116
	v_ashrrev_i32_e32 v242, 3, v132
	v_ashrrev_i32_e32 v246, 3, v194
	v_add_u32_e32 v112, s10, v146
	v_add_u32_e32 v128, s10, v148
	v_add_u32_e32 v190, s10, v242
	v_add_u32_e32 v206, s10, v246
	v_lshlrev_b32_e32 v104, 11, v146
	v_ashrrev_i32_e32 v105, 2, v112
	v_lshlrev_b32_e32 v120, 11, v148
	v_ashrrev_i32_e32 v121, 2, v128
	v_lshlrev_b32_e32 v124, 9, v148
	v_ashrrev_i32_e32 v125, 4, v128
	v_lshlrev_b32_e32 v136, 11, v242
	v_ashrrev_i32_e32 v137, 2, v190
	v_lshlrev_b32_e32 v140, 9, v242
	v_ashrrev_i32_e32 v141, 4, v190
	v_lshlrev_b32_e32 v198, 11, v246
	v_ashrrev_i32_e32 v199, 2, v206
	v_lshlrev_b32_e32 v202, 9, v246
	v_ashrrev_i32_e32 v203, 4, v206
; #define CMB(f) { const float lo = (w0 * bflo(og[q][0].f) + w1 * bflo(og[q][1].f) + w2 * bflo(og[q][2].f)) * bflo(z.f); const float hi = (w0 * bfhi(og[q][0].f) + w1 * bfhi(og[q][1].f) + w2 * bfhi(og[q][2].f)) * bfhi(z.f); o.f = cvtpk(lo, hi); }
; __device__ __forceinline__ void attnA_unit(LAS unsigned char* lds, const Args& A, int unit) {
;     ...
; #pragma unroll
;         for (int q = 0; q < 4; ++q) {
;             const int e = (it0 + q) * 512 + tid, tl = e >> 3, ch = e & 7, s = c * 1024 + tl;
; #pragma unroll
;             for (int g = 0; g < 3; ++g) { const int lg = 2 * g, p = ((s & ((1 << lg) - 1)) << (13 - lg)) | (s >> lg);
;                 ls2[q][g] = LSE[(size_t)((g * 4 + b) * 8 + h) * 8192 + p];
;                 og[q][g] = *(const u32x4*)((const bf16*)(A.ws + WS_QA) + ((size_t)((b * 3 + g) * 8 + h) * 8192 + p) * 64 + ch * 8); }
;             zv[q] = *(const u32x4*)(SAZ + (size_t)(b * 8192 + s) * 512 + h * 64 + ch * 8);
;         }
; #pragma unroll
;         for (int q = 0; q < 4; ++q) {
;             const int e = (it0 + q) * 512 + tid, tl = e >> 3, ch = e & 7, s = c * 1024 + tl;
;             const float M = fmaxf(ls2[q][0], fmaxf(ls2[q][1], ls2[q][2]));
;             float w0 = __builtin_amdgcn_exp2f(ls2[q][0] - M), w1 = __builtin_amdgcn_exp2f(ls2[q][1] - M), w2 = __builtin_amdgcn_exp2f(ls2[q][2] - M);
;             const float wi = 1.0f / (w0 + w1 + w2); w0 *= wi; w1 *= wi; w2 *= wi;
;             const u32x4 z = zv[q]; u32x4 o;
;     ...
;             CMB(x) CMB(y) CMB(z) CMB(w)
	v_and_or_b32 v104, v104, s89, v105
	v_lshlrev_b32_e32 v108, 9, v146
	v_ashrrev_i32_e32 v109, 4, v112
	v_and_or_b32 v120, v120, s89, v121
	v_and_or_b32 v124, v124, s50, v125
	v_and_or_b32 v136, v136, s89, v137
	v_and_or_b32 v140, v140, s50, v141
	v_and_or_b32 v198, v198, s89, v199
	v_and_or_b32 v202, v202, s50, v203
	v_ashrrev_i32_e32 v105, 31, v104
	v_and_or_b32 v108, v108, s50, v109
	v_ashrrev_i32_e32 v121, 31, v120
	v_ashrrev_i32_e32 v125, 31, v124
	v_ashrrev_i32_e32 v137, 31, v136
	v_ashrrev_i32_e32 v141, 31, v140
	v_ashrrev_i32_e32 v199, 31, v198
	v_ashrrev_i32_e32 v203, 31, v202
	v_ashrrev_i32_e32 v113, 31, v112
	v_lshl_add_u64 v[106:107], v[104:105], 2, s[6:7]
	v_lshlrev_b64 v[104:105], 7, v[104:105]
	v_ashrrev_i32_e32 v109, 31, v108
	v_ashrrev_i32_e32 v129, 31, v128
	v_lshl_add_u64 v[122:123], v[120:121], 2, s[6:7]
	v_lshlrev_b64 v[120:121], 7, v[120:121]
	v_lshl_add_u64 v[126:127], v[124:125], 2, s[8:9]
	v_lshlrev_b64 v[124:125], 7, v[124:125]
	v_ashrrev_i32_e32 v191, 31, v190
	v_lshl_add_u64 v[138:139], v[136:137], 2, s[6:7]
	v_lshlrev_b64 v[136:137], 7, v[136:137]
	v_lshl_add_u64 v[142:143], v[140:141], 2, s[8:9]
	v_lshlrev_b64 v[140:141], 7, v[140:141]
	v_ashrrev_i32_e32 v207, 31, v206
	v_lshl_add_u64 v[200:201], v[198:199], 2, s[6:7]
	v_lshlrev_b64 v[198:199], 7, v[198:199]
	v_lshl_add_u64 v[204:205], v[202:203], 2, s[8:9]
	v_lshlrev_b64 v[202:203], 7, v[202:203]
	v_lshl_add_u64 v[100:101], v[112:113], 2, s[4:5]
	v_lshl_add_u64 v[104:105], v[70:71], 0, v[104:105]
	v_lshl_add_u64 v[110:111], v[108:109], 2, s[8:9]
	v_lshl_add_u64 v[116:117], v[128:129], 2, s[4:5]
	v_lshl_add_u64 v[120:121], v[70:71], 0, v[120:121]
	v_lshl_add_u64 v[124:125], v[72:73], 0, v[124:125]
	v_lshl_add_u64 v[132:133], v[190:191], 2, s[4:5]
	v_lshl_add_u64 v[136:137], v[70:71], 0, v[136:137]
	v_lshl_add_u64 v[140:141], v[72:73], 0, v[140:141]
	v_lshl_add_u64 v[194:195], v[206:207], 2, s[4:5]
	v_lshl_add_u64 v[198:199], v[70:71], 0, v[198:199]
	v_lshl_add_u64 v[202:203], v[72:73], 0, v[202:203]
	global_load_dword v147, v[100:101], off
	global_load_dword v152, v[110:111], off
	global_load_dword v149, v[106:107], off
	global_load_dword v155, v[116:117], off
	global_load_dword v240, v[122:123], off
	global_load_dword v243, v[132:133], off
	global_load_dword v241, v[126:127], off
	global_load_dword v244, v[138:139], off
	global_load_dword v247, v[194:195], off
	global_load_dword v245, v[142:143], off
	global_load_dword v248, v[200:201], off
	global_load_dword v249, v[204:205], off
	v_lshlrev_b64 v[108:109], 7, v[108:109]
	global_load_dwordx4 v[202:205], v[202:203], off
	v_lshl_add_u64 v[108:109], v[72:73], 0, v[108:109]
	global_load_dwordx4 v[198:201], v[198:199], off
	v_lshlrev_b64 v[132:133], 7, v[190:191]
	global_load_dwordx4 v[140:143], v[140:141], off
	v_lshl_add_u64 v[132:133], v[68:69], 0, v[132:133]
	global_load_dwordx4 v[136:139], v[136:137], off
	v_add_u32_e32 v190, s11, v190
	global_load_dwordx4 v[124:127], v[124:125], off
	v_ashrrev_i32_e32 v191, 31, v190
	global_load_dwordx4 v[120:123], v[120:121], off
	v_lshlrev_b64 v[116:117], 7, v[128:129]
	global_load_dwordx4 v[104:107], v[104:105], off
	v_lshlrev_b64 v[100:101], 7, v[112:113]
	v_lshl_add_u64 v[100:101], v[68:69], 0, v[100:101]
	v_add_u32_e32 v112, s11, v112
	global_load_dwordx4 v[100:103], v[100:101], off
	v_ashrrev_i32_e32 v113, 31, v112
	v_lshlrev_b64 v[112:113], 10, v[112:113]
	global_load_dwordx4 v[108:111], v[108:109], off
	v_lshl_add_u64 v[112:113], v[64:65], 0, v[112:113]
	global_load_dwordx4 v[112:115], v[112:113], off
	v_lshl_add_u64 v[116:117], v[68:69], 0, v[116:117]
	global_load_dwordx4 v[116:119], v[116:117], off
	v_add_u32_e32 v128, s11, v128
	v_ashrrev_i32_e32 v129, 31, v128
	v_lshlrev_b64 v[128:129], 10, v[128:129]
	v_lshl_add_u64 v[128:129], v[64:65], 0, v[128:129]
	global_load_dwordx4 v[128:131], v[128:129], off
	v_lshlrev_b64 v[190:191], 10, v[190:191]
	global_load_dwordx4 v[132:135], v[132:133], off
	v_lshl_add_u64 v[190:191], v[64:65], 0, v[190:191]
	global_load_dwordx4 v[190:193], v[190:191], off
	v_lshlrev_b64 v[194:195], 7, v[206:207]
	v_add_u32_e32 v206, s11, v206
	v_ashrrev_i32_e32 v207, 31, v206
	v_lshlrev_b64 v[206:207], 10, v[206:207]
	v_lshl_add_u64 v[194:195], v[68:69], 0, v[194:195]
	v_lshl_add_u64 v[206:207], v[64:65], 0, v[206:207]
	global_load_dwordx4 v[194:197], v[194:195], off
	global_load_dwordx4 v[206:209], v[206:207], off
	v_add_u32_e32 v145, 0x800, v145
	s_waitcnt vmcnt(53)
	v_max3_f32 v81, v75, v77, v80
	v_sub_f32_e32 v75, v75, v81
	v_exp_f32_e32 v79, v75
	v_sub_f32_e32 v75, v77, v81
	v_exp_f32_e32 v78, v75
	v_sub_f32_e32 v75, v80, v81
	v_exp_f32_e32 v75, v75
	v_add_f32_e32 v77, v79, v78
	v_add_f32_e32 v77, v75, v77
	v_div_scale_f32 v80, s[14:15], v77, v77, 1.0
	v_rcp_f32_e32 v81, v80
	s_waitcnt vmcnt(35)
	v_lshlrev_b32_e32 v86, 16, v8
	v_fma_f32 v82, -v80, v81, 1.0
	v_fmac_f32_e32 v81, v82, v81
	v_div_scale_f32 v82, vcc, 1.0, v77, 1.0
	v_mul_f32_e32 v84, v82, v81
	v_fma_f32 v85, -v80, v84, v82
	v_fmac_f32_e32 v84, v85, v81
	v_fma_f32 v80, -v80, v84, v82
	v_div_fmas_f32 v80, v80, v81, v84
	v_div_fixup_f32 v80, v80, v77, 1.0
	v_pk_mul_f32 v[78:79], v[78:79], v[80:81] op_sel_hi:[1,0]
	v_lshlrev_b32_e32 v84, 16, v0
	v_and_b32_e32 v85, 0xffff0000, v4
	v_mul_f32_e32 v82, v75, v80
	v_lshlrev_b32_e32 v80, 16, v4
	v_and_b32_e32 v81, 0xffff0000, v0
	v_pk_mul_f32 v[84:85], v[78:79], v[84:85] op_sel:[1,0] op_sel_hi:[0,1]
	v_and_b32_e32 v87, 0xffff0000, v8
	v_pk_fma_f32 v[80:81], v[78:79], v[80:81], v[84:85]
	s_waitcnt vmcnt(34)
; #define CMB(f) { const float lo = (w0 * bflo(og[q][0].f) + w1 * bflo(og[q][1].f) + w2 * bflo(og[q][2].f)) * bflo(z.f); const float hi = (w0 * bfhi(og[q][0].f) + w1 * bfhi(og[q][1].f) + w2 * bfhi(og[q][2].f)) * bfhi(z.f); o.f = cvtpk(lo, hi); }
; __device__ __forceinline__ void attnA_unit(LAS unsigned char* lds, const Args& A, int unit) {
;     ...
;         for (int q = 0; q < 4; ++q) {
;             const int e = (it0 + q) * 512 + tid, tl = e >> 3, ch = e & 7, s = c * 1024 + tl;
;             const float M = fmaxf(ls2[q][0], fmaxf(ls2[q][1], ls2[q][2]));
;             float w0 = __builtin_amdgcn_exp2f(ls2[q][0] - M), w1 = __builtin_amdgcn_exp2f(ls2[q][1] - M), w2 = __builtin_amdgcn_exp2f(ls2[q][2] - M);
;             const float wi = 1.0f / (w0 + w1 + w2); w0 *= wi; w1 *= wi; w2 *= wi;
;             const u32x4 z = zv[q]; u32x4 o;
;     ...
;             CMB(x) CMB(y) CMB(z) CMB(w)
;     ...
;             *(u32x4*)(SAZ + (size_t)(b * 8192 + s) * 512 + h * 64 + ch * 8) = o;
	v_lshlrev_b32_e32 v88, 16, v12
	v_and_b32_e32 v89, 0xffff0000, v12
	v_pk_fma_f32 v[80:81], v[82:83], v[86:87], v[80:81] op_sel_hi:[0,1,1]
	v_pk_mul_f32 v[80:81], v[80:81], v[88:89]
	v_lshlrev_b32_e32 v4, 16, v1
	v_cvt_pk_bf16_f32 v0, v80, v81
	v_lshlrev_b32_e32 v80, 16, v5
	v_and_b32_e32 v5, 0xffff0000, v5
	v_and_b32_e32 v81, 0xffff0000, v1
	v_pk_mul_f32 v[4:5], v[78:79], v[4:5] op_sel:[1,0] op_sel_hi:[0,1]
	v_lshlrev_b32_e32 v8, 16, v9
	v_and_b32_e32 v9, 0xffff0000, v9
	v_pk_fma_f32 v[4:5], v[78:79], v[80:81], v[4:5]
	v_lshlrev_b32_e32 v12, 16, v13
	v_and_b32_e32 v13, 0xffff0000, v13
	v_pk_fma_f32 v[4:5], v[82:83], v[8:9], v[4:5] op_sel_hi:[0,1,1]
	v_pk_mul_f32 v[4:5], v[4:5], v[12:13]
	v_lshlrev_b32_e32 v8, 16, v2
	v_and_b32_e32 v9, 0xffff0000, v6
	v_cvt_pk_bf16_f32 v1, v4, v5
	v_lshlrev_b32_e32 v4, 16, v6
	v_and_b32_e32 v5, 0xffff0000, v2
	v_pk_mul_f32 v[8:9], v[78:79], v[8:9] op_sel:[1,0] op_sel_hi:[0,1]
	v_lshlrev_b32_e32 v12, 16, v10
	v_and_b32_e32 v13, 0xffff0000, v10
	v_pk_fma_f32 v[4:5], v[78:79], v[4:5], v[8:9]
	v_lshlrev_b32_e32 v80, 16, v14
	v_and_b32_e32 v81, 0xffff0000, v14
	v_pk_fma_f32 v[4:5], v[82:83], v[12:13], v[4:5] op_sel_hi:[0,1,1]
	v_pk_mul_f32 v[4:5], v[4:5], v[80:81]
	v_lshlrev_b32_e32 v6, 16, v3
	v_cvt_pk_bf16_f32 v2, v4, v5
	v_lshlrev_b32_e32 v4, 16, v7
	v_and_b32_e32 v7, 0xffff0000, v7
	v_and_b32_e32 v5, 0xffff0000, v3
	v_pk_mul_f32 v[6:7], v[78:79], v[6:7] op_sel:[1,0] op_sel_hi:[0,1]
	v_pk_fma_f32 v[4:5], v[78:79], v[4:5], v[6:7]
	v_lshlrev_b32_e32 v6, 16, v11
	v_and_b32_e32 v7, 0xffff0000, v11
	v_pk_fma_f32 v[4:5], v[82:83], v[6:7], v[4:5] op_sel_hi:[0,1,1]
	v_lshlrev_b32_e32 v6, 16, v15
	v_and_b32_e32 v7, 0xffff0000, v15
	v_pk_mul_f32 v[4:5], v[4:5], v[6:7]
	v_and_b32_e32 v9, 0xffff0000, v24
	v_cvt_pk_bf16_f32 v3, v4, v5
	v_add_u32_e32 v4, s12, v74
	v_ashrrev_i32_e32 v5, 31, v4
	v_lshlrev_b64 v[4:5], 10, v[4:5]
	v_lshl_add_u64 v[4:5], v[66:67], 0, v[4:5]
	global_store_dwordx4 v[4:5], v[0:3], off
	s_waitcnt vmcnt(33)
	v_lshlrev_b32_e32 v10, 16, v28
	v_and_b32_e32 v11, 0xffff0000, v28
	v_max3_f32 v2, v83, v90, v91
	v_sub_f32_e32 v0, v83, v2
	v_exp_f32_e32 v1, v0
	v_sub_f32_e32 v0, v90, v2
	v_exp_f32_e32 v0, v0
	v_sub_f32_e32 v2, v91, v2
	v_exp_f32_e32 v3, v2
	v_lshlrev_b32_e32 v12, 16, v29
	v_add_f32_e32 v2, v1, v0
	v_and_b32_e32 v13, 0xffff0000, v29
	v_add_f32_e32 v2, v3, v2
	v_div_scale_f32 v4, s[14:15], v2, v2, 1.0
	v_rcp_f32_e32 v5, v4
	s_nop 0
	v_fma_f32 v6, -v4, v5, 1.0
	v_fmac_f32_e32 v5, v6, v5
	v_div_scale_f32 v6, vcc, 1.0, v2, 1.0
	v_mul_f32_e32 v7, v6, v5
	v_fma_f32 v8, -v4, v7, v6
	v_fmac_f32_e32 v7, v8, v5
	v_fma_f32 v4, -v4, v7, v6
	v_div_fmas_f32 v4, v4, v5, v7
	v_div_fixup_f32 v2, v4, v2, 1.0
	v_mul_f32_e32 v4, v3, v2
	v_pk_mul_f32 v[6:7], v[0:1], v[2:3] op_sel_hi:[1,0]
	v_lshlrev_b32_e32 v2, 16, v16
	v_and_b32_e32 v3, 0xffff0000, v20
	v_lshlrev_b32_e32 v0, 16, v20
	v_and_b32_e32 v1, 0xffff0000, v16
	v_pk_mul_f32 v[2:3], v[6:7], v[2:3] op_sel:[1,0] op_sel_hi:[0,1]
	v_lshlrev_b32_e32 v8, 16, v24
	v_pk_fma_f32 v[0:1], v[6:7], v[0:1], v[2:3]
	v_lshlrev_b32_e32 v2, 16, v21
	v_pk_fma_f32 v[0:1], v[4:5], v[8:9], v[0:1] op_sel_hi:[0,1,1]
	v_lshlrev_b32_e32 v8, 16, v17
	v_and_b32_e32 v9, 0xffff0000, v21
	v_and_b32_e32 v3, 0xffff0000, v17
	v_pk_mul_f32 v[8:9], v[6:7], v[8:9] op_sel:[1,0] op_sel_hi:[0,1]
	v_pk_mul_f32 v[0:1], v[0:1], v[10:11]
	v_lshlrev_b32_e32 v10, 16, v25
	v_and_b32_e32 v11, 0xffff0000, v25
	v_pk_fma_f32 v[2:3], v[6:7], v[2:3], v[8:9]
	v_lshlrev_b32_e32 v8, 16, v18
	v_pk_fma_f32 v[2:3], v[4:5], v[10:11], v[2:3] op_sel_hi:[0,1,1]
	v_pk_mul_f32 v[2:3], v[2:3], v[12:13]
	v_and_b32_e32 v9, 0xffff0000, v22
	v_cvt_pk_bf16_f32 v0, v0, v1
	v_cvt_pk_bf16_f32 v1, v2, v3
	v_lshlrev_b32_e32 v2, 16, v22
	v_and_b32_e32 v3, 0xffff0000, v18
	v_pk_mul_f32 v[8:9], v[6:7], v[8:9] op_sel:[1,0] op_sel_hi:[0,1]
	v_lshlrev_b32_e32 v10, 16, v26
	v_and_b32_e32 v11, 0xffff0000, v26
	v_pk_fma_f32 v[2:3], v[6:7], v[2:3], v[8:9]
	v_lshlrev_b32_e32 v8, 16, v23
	v_pk_fma_f32 v[2:3], v[4:5], v[10:11], v[2:3] op_sel_hi:[0,1,1]
	v_lshlrev_b32_e32 v10, 16, v19
	v_and_b32_e32 v11, 0xffff0000, v23
	v_and_b32_e32 v9, 0xffff0000, v19
	v_pk_mul_f32 v[10:11], v[6:7], v[10:11] op_sel:[1,0] op_sel_hi:[0,1]
	v_pk_fma_f32 v[6:7], v[6:7], v[8:9], v[10:11]
	v_lshlrev_b32_e32 v8, 16, v27
	v_and_b32_e32 v9, 0xffff0000, v27
	v_lshlrev_b32_e32 v12, 16, v30
	v_and_b32_e32 v13, 0xffff0000, v30
	v_pk_fma_f32 v[4:5], v[4:5], v[8:9], v[6:7] op_sel_hi:[0,1,1]
	v_lshlrev_b32_e32 v6, 16, v31
	v_and_b32_e32 v7, 0xffff0000, v31
	v_pk_mul_f32 v[2:3], v[2:3], v[12:13]
	v_pk_mul_f32 v[4:5], v[4:5], v[6:7]
	v_cvt_pk_bf16_f32 v2, v2, v3
	v_cvt_pk_bf16_f32 v3, v4, v5
	v_add_u32_e32 v4, s12, v76
	v_ashrrev_i32_e32 v5, 31, v4
	v_lshlrev_b64 v[4:5], 10, v[4:5]
	v_lshl_add_u64 v[4:5], v[66:67], 0, v[4:5]
	global_store_dwordx4 v[4:5], v[0:3], off
	v_and_b32_e32 v9, 0xffff0000, v40
	s_waitcnt vmcnt(32)
; #define CMB(f) { const float lo = (w0 * bflo(og[q][0].f) + w1 * bflo(og[q][1].f) + w2 * bflo(og[q][2].f)) * bflo(z.f); const float hi = (w0 * bfhi(og[q][0].f) + w1 * bfhi(og[q][1].f) + w2 * bfhi(og[q][2].f)) * bfhi(z.f); o.f = cvtpk(lo, hi); }
; __device__ __forceinline__ void attnA_unit(LAS unsigned char* lds, const Args& A, int unit) {
;     ...
;         for (int q = 0; q < 4; ++q) {
;             const int e = (it0 + q) * 512 + tid, tl = e >> 3, ch = e & 7, s = c * 1024 + tl;
;             const float M = fmaxf(ls2[q][0], fmaxf(ls2[q][1], ls2[q][2]));
;             float w0 = __builtin_amdgcn_exp2f(ls2[q][0] - M), w1 = __builtin_amdgcn_exp2f(ls2[q][1] - M), w2 = __builtin_amdgcn_exp2f(ls2[q][2] - M);
;             const float wi = 1.0f / (w0 + w1 + w2); w0 *= wi; w1 *= wi; w2 *= wi;
;             const u32x4 z = zv[q]; u32x4 o;
;     ...
;             CMB(x) CMB(y) CMB(z) CMB(w)
;     ...
;             *(u32x4*)(SAZ + (size_t)(b * 8192 + s) * 512 + h * 64 + ch * 8) = o;
	v_lshlrev_b32_e32 v10, 16, v44
	v_max3_f32 v2, v93, v94, v95
	v_sub_f32_e32 v0, v93, v2
	v_exp_f32_e32 v1, v0
	v_sub_f32_e32 v0, v94, v2
	v_exp_f32_e32 v0, v0
	v_sub_f32_e32 v2, v95, v2
	v_exp_f32_e32 v3, v2
	v_and_b32_e32 v11, 0xffff0000, v44
	v_add_f32_e32 v2, v1, v0
	v_lshlrev_b32_e32 v12, 16, v45
	v_add_f32_e32 v2, v3, v2
	v_div_scale_f32 v4, s[14:15], v2, v2, 1.0
	v_rcp_f32_e32 v5, v4
	v_and_b32_e32 v13, 0xffff0000, v45
	v_fma_f32 v6, -v4, v5, 1.0
	v_fmac_f32_e32 v5, v6, v5
	v_div_scale_f32 v6, vcc, 1.0, v2, 1.0
	v_mul_f32_e32 v7, v6, v5
	v_fma_f32 v8, -v4, v7, v6
	v_fmac_f32_e32 v7, v8, v5
	v_fma_f32 v4, -v4, v7, v6
	v_div_fmas_f32 v4, v4, v5, v7
	v_div_fixup_f32 v2, v4, v2, 1.0
	v_mul_f32_e32 v4, v3, v2
	v_pk_mul_f32 v[6:7], v[0:1], v[2:3] op_sel_hi:[1,0]
	v_lshlrev_b32_e32 v2, 16, v32
	v_and_b32_e32 v3, 0xffff0000, v36
	v_lshlrev_b32_e32 v0, 16, v36
	v_and_b32_e32 v1, 0xffff0000, v32
	v_pk_mul_f32 v[2:3], v[6:7], v[2:3] op_sel:[1,0] op_sel_hi:[0,1]
	v_lshlrev_b32_e32 v8, 16, v40
	v_pk_fma_f32 v[0:1], v[6:7], v[0:1], v[2:3]
	v_lshlrev_b32_e32 v2, 16, v37
	v_pk_fma_f32 v[0:1], v[4:5], v[8:9], v[0:1] op_sel_hi:[0,1,1]
	v_lshlrev_b32_e32 v8, 16, v33
	v_and_b32_e32 v9, 0xffff0000, v37
	v_and_b32_e32 v3, 0xffff0000, v33
	v_pk_mul_f32 v[8:9], v[6:7], v[8:9] op_sel:[1,0] op_sel_hi:[0,1]
	v_pk_mul_f32 v[0:1], v[0:1], v[10:11]
	v_lshlrev_b32_e32 v10, 16, v41
	v_and_b32_e32 v11, 0xffff0000, v41
	v_pk_fma_f32 v[2:3], v[6:7], v[2:3], v[8:9]
	v_lshlrev_b32_e32 v8, 16, v34
	v_pk_fma_f32 v[2:3], v[4:5], v[10:11], v[2:3] op_sel_hi:[0,1,1]
	v_pk_mul_f32 v[2:3], v[2:3], v[12:13]
	v_and_b32_e32 v9, 0xffff0000, v38
	v_cvt_pk_bf16_f32 v0, v0, v1
	v_cvt_pk_bf16_f32 v1, v2, v3
	v_lshlrev_b32_e32 v2, 16, v38
	v_and_b32_e32 v3, 0xffff0000, v34
	v_pk_mul_f32 v[8:9], v[6:7], v[8:9] op_sel:[1,0] op_sel_hi:[0,1]
	v_lshlrev_b32_e32 v10, 16, v42
	v_and_b32_e32 v11, 0xffff0000, v42
	v_pk_fma_f32 v[2:3], v[6:7], v[2:3], v[8:9]
	v_lshlrev_b32_e32 v8, 16, v39
	v_pk_fma_f32 v[2:3], v[4:5], v[10:11], v[2:3] op_sel_hi:[0,1,1]
	v_lshlrev_b32_e32 v10, 16, v35
	v_and_b32_e32 v11, 0xffff0000, v39
	v_and_b32_e32 v9, 0xffff0000, v35
	v_pk_mul_f32 v[10:11], v[6:7], v[10:11] op_sel:[1,0] op_sel_hi:[0,1]
	v_pk_fma_f32 v[6:7], v[6:7], v[8:9], v[10:11]
	v_lshlrev_b32_e32 v8, 16, v43
	v_and_b32_e32 v9, 0xffff0000, v43
	v_lshlrev_b32_e32 v12, 16, v46
	v_and_b32_e32 v13, 0xffff0000, v46
	v_pk_fma_f32 v[4:5], v[4:5], v[8:9], v[6:7] op_sel_hi:[0,1,1]
	v_lshlrev_b32_e32 v6, 16, v47
	v_and_b32_e32 v7, 0xffff0000, v47
	v_pk_mul_f32 v[2:3], v[2:3], v[12:13]
	v_pk_mul_f32 v[4:5], v[4:5], v[6:7]
	v_cvt_pk_bf16_f32 v2, v2, v3
	v_cvt_pk_bf16_f32 v3, v4, v5
	v_add_u32_e32 v4, s12, v92
	v_ashrrev_i32_e32 v5, 31, v4
	v_lshlrev_b64 v[4:5], 10, v[4:5]
	v_lshl_add_u64 v[4:5], v[66:67], 0, v[4:5]
	global_store_dwordx4 v[4:5], v[0:3], off
	v_and_b32_e32 v9, 0xffff0000, v56
	s_waitcnt vmcnt(31)
	v_lshlrev_b32_e32 v10, 16, v60
	v_max3_f32 v2, v97, v98, v99
	v_sub_f32_e32 v0, v97, v2
	v_exp_f32_e32 v1, v0
	v_sub_f32_e32 v0, v98, v2
	v_exp_f32_e32 v0, v0
	v_sub_f32_e32 v2, v99, v2
	v_exp_f32_e32 v3, v2
	v_and_b32_e32 v11, 0xffff0000, v60
	v_add_f32_e32 v2, v1, v0
	v_lshlrev_b32_e32 v12, 16, v61
	v_add_f32_e32 v2, v3, v2
	v_div_scale_f32 v4, s[14:15], v2, v2, 1.0
	v_rcp_f32_e32 v5, v4
	v_and_b32_e32 v13, 0xffff0000, v61
	v_fma_f32 v6, -v4, v5, 1.0
	v_fmac_f32_e32 v5, v6, v5
	v_div_scale_f32 v6, vcc, 1.0, v2, 1.0
	v_mul_f32_e32 v7, v6, v5
	v_fma_f32 v8, -v4, v7, v6
	v_fmac_f32_e32 v7, v8, v5
	v_fma_f32 v4, -v4, v7, v6
	v_div_fmas_f32 v4, v4, v5, v7
	v_div_fixup_f32 v2, v4, v2, 1.0
	v_mul_f32_e32 v4, v3, v2
	v_pk_mul_f32 v[6:7], v[0:1], v[2:3] op_sel_hi:[1,0]
	v_lshlrev_b32_e32 v2, 16, v48
	v_and_b32_e32 v3, 0xffff0000, v52
	v_lshlrev_b32_e32 v0, 16, v52
	v_and_b32_e32 v1, 0xffff0000, v48
	v_pk_mul_f32 v[2:3], v[6:7], v[2:3] op_sel:[1,0] op_sel_hi:[0,1]
	v_lshlrev_b32_e32 v8, 16, v56
	v_pk_fma_f32 v[0:1], v[6:7], v[0:1], v[2:3]
	v_lshlrev_b32_e32 v2, 16, v53
	v_pk_fma_f32 v[0:1], v[4:5], v[8:9], v[0:1] op_sel_hi:[0,1,1]
	v_lshlrev_b32_e32 v8, 16, v49
	v_and_b32_e32 v9, 0xffff0000, v53
	v_and_b32_e32 v3, 0xffff0000, v49
	v_pk_mul_f32 v[8:9], v[6:7], v[8:9] op_sel:[1,0] op_sel_hi:[0,1]
	v_pk_mul_f32 v[0:1], v[0:1], v[10:11]
	v_lshlrev_b32_e32 v10, 16, v57
	v_and_b32_e32 v11, 0xffff0000, v57
	v_pk_fma_f32 v[2:3], v[6:7], v[2:3], v[8:9]
	v_lshlrev_b32_e32 v8, 16, v50
	v_pk_fma_f32 v[2:3], v[4:5], v[10:11], v[2:3] op_sel_hi:[0,1,1]
	v_pk_mul_f32 v[2:3], v[2:3], v[12:13]
	v_and_b32_e32 v9, 0xffff0000, v54
	v_cvt_pk_bf16_f32 v0, v0, v1
	v_cvt_pk_bf16_f32 v1, v2, v3
	v_lshlrev_b32_e32 v2, 16, v54
	v_and_b32_e32 v3, 0xffff0000, v50
	v_pk_mul_f32 v[8:9], v[6:7], v[8:9] op_sel:[1,0] op_sel_hi:[0,1]
	v_lshlrev_b32_e32 v10, 16, v58
	v_and_b32_e32 v11, 0xffff0000, v58
	v_pk_fma_f32 v[2:3], v[6:7], v[2:3], v[8:9]
	v_lshlrev_b32_e32 v8, 16, v55
	v_pk_fma_f32 v[2:3], v[4:5], v[10:11], v[2:3] op_sel_hi:[0,1,1]
	v_lshlrev_b32_e32 v10, 16, v51
	v_and_b32_e32 v11, 0xffff0000, v55
	v_and_b32_e32 v9, 0xffff0000, v51
	v_pk_mul_f32 v[10:11], v[6:7], v[10:11] op_sel:[1,0] op_sel_hi:[0,1]
	v_pk_fma_f32 v[6:7], v[6:7], v[8:9], v[10:11]
	v_lshlrev_b32_e32 v8, 16, v59
	v_and_b32_e32 v9, 0xffff0000, v59
	v_lshlrev_b32_e32 v12, 16, v62
	v_and_b32_e32 v13, 0xffff0000, v62
	v_pk_fma_f32 v[4:5], v[4:5], v[8:9], v[6:7] op_sel_hi:[0,1,1]
	v_lshlrev_b32_e32 v6, 16, v63
	v_and_b32_e32 v7, 0xffff0000, v63
	v_pk_mul_f32 v[2:3], v[2:3], v[12:13]
	v_pk_mul_f32 v[4:5], v[4:5], v[6:7]
	v_cvt_pk_bf16_f32 v2, v2, v3
	v_cvt_pk_bf16_f32 v3, v4, v5
	v_add_u32_e32 v4, s12, v96
	v_ashrrev_i32_e32 v5, 31, v4
	v_lshlrev_b64 v[4:5], 10, v[4:5]
; __device__ __forceinline__ void attnA_unit(LAS unsigned char* lds, const Args& A, int unit) {
;     ...
;     for (int it0 = 0; it0 < 16; it0 += 4) {
;         float ls2[4][3]; u32x4 og[4][3], zv[4];
; #pragma unroll
;         for (int q = 0; q < 4; ++q) {
;             const int e = (it0 + q) * 512 + tid, tl = e >> 3, ch = e & 7, s = c * 1024 + tl;
; #pragma unroll
;             for (int g = 0; g < 3; ++g) { const int lg = 2 * g, p = ((s & ((1 << lg) - 1)) << (13 - lg)) | (s >> lg);
;                 ls2[q][g] = LSE[(size_t)((g * 4 + b) * 8 + h) * 8192 + p];
;                 og[q][g] = *(const u32x4*)((const bf16*)(A.ws + WS_QA) + ((size_t)((b * 3 + g) * 8 + h) * 8192 + p) * 64 + ch * 8); }
;             zv[q] = *(const u32x4*)(SAZ + (size_t)(b * 8192 + s) * 512 + h * 64 + ch * 8);
;         }
; #pragma unroll
;         for (int q = 0; q < 4; ++q) {
;             const int e = (it0 + q) * 512 + tid, tl = e >> 3, ch = e & 7, s = c * 1024 + tl;
;             const float M = fmaxf(ls2[q][0], fmaxf(ls2[q][1], ls2[q][2]));
;             float w0 = __builtin_amdgcn_exp2f(ls2[q][0] - M), w1 = __builtin_amdgcn_exp2f(ls2[q][1] - M), w2 = __builtin_amdgcn_exp2f(ls2[q][2] - M);
;             const float wi = 1.0f / (w0 + w1 + w2); w0 *= wi; w1 *= wi; w2 *= wi;
	v_lshl_add_u64 v[4:5], v[66:67], 0, v[4:5]
	global_store_dwordx4 v[4:5], v[0:3], off
	v_add_u32_e32 v16, 0x200, v145
	v_add_u32_e32 v32, 0x400, v145
	v_add_u32_e32 v48, 0x600, v145
	v_ashrrev_i32_e32 v74, 3, v145
	v_ashrrev_i32_e32 v76, 3, v16
	v_ashrrev_i32_e32 v92, 3, v32
	v_ashrrev_i32_e32 v96, 3, v48
	v_add_u32_e32 v12, s10, v74
	v_add_u32_e32 v28, s10, v76
	v_add_u32_e32 v44, s10, v92
	v_add_u32_e32 v60, s10, v96
	v_lshlrev_b32_e32 v4, 11, v74
	v_ashrrev_i32_e32 v5, 2, v12
	v_lshlrev_b32_e32 v20, 11, v76
	v_ashrrev_i32_e32 v21, 2, v28
	v_lshlrev_b32_e32 v24, 9, v76
	v_ashrrev_i32_e32 v25, 4, v28
	v_lshlrev_b32_e32 v36, 11, v92
	v_ashrrev_i32_e32 v37, 2, v44
	v_lshlrev_b32_e32 v40, 9, v92
	v_ashrrev_i32_e32 v41, 4, v44
	v_lshlrev_b32_e32 v52, 11, v96
	v_ashrrev_i32_e32 v53, 2, v60
	v_lshlrev_b32_e32 v56, 9, v96
	v_ashrrev_i32_e32 v57, 4, v60
	v_and_or_b32 v4, v4, s89, v5
	v_lshlrev_b32_e32 v8, 9, v74
	v_ashrrev_i32_e32 v9, 4, v12
	v_and_or_b32 v20, v20, s89, v21
	v_and_or_b32 v24, v24, s50, v25
	v_and_or_b32 v36, v36, s89, v37
	v_and_or_b32 v40, v40, s50, v41
	v_and_or_b32 v52, v52, s89, v53
	v_and_or_b32 v56, v56, s50, v57
	v_ashrrev_i32_e32 v5, 31, v4
	v_and_or_b32 v8, v8, s50, v9
	v_ashrrev_i32_e32 v21, 31, v20
	v_ashrrev_i32_e32 v25, 31, v24
	v_ashrrev_i32_e32 v37, 31, v36
	v_ashrrev_i32_e32 v41, 31, v40
	v_ashrrev_i32_e32 v53, 31, v52
	v_ashrrev_i32_e32 v57, 31, v56
	v_ashrrev_i32_e32 v13, 31, v12
	v_lshl_add_u64 v[6:7], v[4:5], 2, s[6:7]
	v_lshlrev_b64 v[4:5], 7, v[4:5]
	v_ashrrev_i32_e32 v9, 31, v8
	v_ashrrev_i32_e32 v29, 31, v28
	v_lshl_add_u64 v[22:23], v[20:21], 2, s[6:7]
	v_lshlrev_b64 v[20:21], 7, v[20:21]
	v_lshl_add_u64 v[26:27], v[24:25], 2, s[8:9]
	v_lshlrev_b64 v[24:25], 7, v[24:25]
	v_ashrrev_i32_e32 v45, 31, v44
	v_lshl_add_u64 v[38:39], v[36:37], 2, s[6:7]
	v_lshlrev_b64 v[36:37], 7, v[36:37]
	v_lshl_add_u64 v[42:43], v[40:41], 2, s[8:9]
	v_lshlrev_b64 v[40:41], 7, v[40:41]
	v_ashrrev_i32_e32 v61, 31, v60
	v_lshl_add_u64 v[54:55], v[52:53], 2, s[6:7]
	v_lshlrev_b64 v[52:53], 7, v[52:53]
	v_lshl_add_u64 v[58:59], v[56:57], 2, s[8:9]
	v_lshlrev_b64 v[56:57], 7, v[56:57]
	v_lshl_add_u64 v[0:1], v[12:13], 2, s[4:5]
	v_lshl_add_u64 v[4:5], v[70:71], 0, v[4:5]
	v_lshl_add_u64 v[10:11], v[8:9], 2, s[8:9]
	v_lshl_add_u64 v[16:17], v[28:29], 2, s[4:5]
	v_lshl_add_u64 v[20:21], v[70:71], 0, v[20:21]
	v_lshl_add_u64 v[24:25], v[72:73], 0, v[24:25]
	v_lshl_add_u64 v[32:33], v[44:45], 2, s[4:5]
	v_lshl_add_u64 v[36:37], v[70:71], 0, v[36:37]
	v_lshl_add_u64 v[40:41], v[72:73], 0, v[40:41]
	v_lshl_add_u64 v[48:49], v[60:61], 2, s[4:5]
	v_lshl_add_u64 v[52:53], v[70:71], 0, v[52:53]
	v_lshl_add_u64 v[56:57], v[72:73], 0, v[56:57]
	global_load_dword v75, v[0:1], off
	global_load_dword v80, v[10:11], off
	global_load_dword v77, v[6:7], off
	global_load_dword v83, v[16:17], off
	global_load_dword v90, v[22:23], off
	global_load_dword v93, v[32:33], off
	global_load_dword v91, v[26:27], off
	global_load_dword v94, v[38:39], off
	global_load_dword v97, v[48:49], off
	global_load_dword v95, v[42:43], off
	global_load_dword v98, v[54:55], off
	global_load_dword v99, v[58:59], off
	v_lshlrev_b64 v[8:9], 7, v[8:9]
	global_load_dwordx4 v[56:59], v[56:57], off
	v_lshl_add_u64 v[8:9], v[72:73], 0, v[8:9]
	global_load_dwordx4 v[52:55], v[52:53], off
	v_lshlrev_b64 v[32:33], 7, v[44:45]
	global_load_dwordx4 v[40:43], v[40:41], off
	v_lshl_add_u64 v[32:33], v[68:69], 0, v[32:33]
	global_load_dwordx4 v[36:39], v[36:37], off
	v_add_u32_e32 v44, s11, v44
	global_load_dwordx4 v[24:27], v[24:25], off
	v_ashrrev_i32_e32 v45, 31, v44
	global_load_dwordx4 v[20:23], v[20:21], off
	v_lshlrev_b64 v[16:17], 7, v[28:29]
	global_load_dwordx4 v[4:7], v[4:5], off
	v_lshlrev_b64 v[0:1], 7, v[12:13]
	v_lshl_add_u64 v[0:1], v[68:69], 0, v[0:1]
	v_add_u32_e32 v12, s11, v12
	global_load_dwordx4 v[0:3], v[0:1], off
	v_ashrrev_i32_e32 v13, 31, v12
	v_lshlrev_b64 v[12:13], 10, v[12:13]
	global_load_dwordx4 v[8:11], v[8:9], off
	v_lshl_add_u64 v[12:13], v[64:65], 0, v[12:13]
	global_load_dwordx4 v[12:15], v[12:13], off
	v_lshl_add_u64 v[16:17], v[68:69], 0, v[16:17]
	global_load_dwordx4 v[16:19], v[16:17], off
	v_add_u32_e32 v28, s11, v28
	v_ashrrev_i32_e32 v29, 31, v28
	v_lshlrev_b64 v[28:29], 10, v[28:29]
	v_lshl_add_u64 v[28:29], v[64:65], 0, v[28:29]
	global_load_dwordx4 v[28:31], v[28:29], off
	v_lshlrev_b64 v[44:45], 10, v[44:45]
	global_load_dwordx4 v[32:35], v[32:33], off
	v_lshl_add_u64 v[44:45], v[64:65], 0, v[44:45]
	global_load_dwordx4 v[44:47], v[44:45], off
	v_lshlrev_b64 v[48:49], 7, v[60:61]
	v_add_u32_e32 v60, s11, v60
	v_ashrrev_i32_e32 v61, 31, v60
	v_lshlrev_b64 v[60:61], 10, v[60:61]
	v_lshl_add_u64 v[48:49], v[68:69], 0, v[48:49]
	v_lshl_add_u64 v[60:61], v[64:65], 0, v[60:61]
	global_load_dwordx4 v[48:51], v[48:49], off
	global_load_dwordx4 v[60:63], v[60:61], off
	v_add_u32_e32 v145, 0x800, v145
	s_waitcnt vmcnt(57)
	v_max3_f32 v153, v147, v149, v152
	v_sub_f32_e32 v147, v147, v153
	v_exp_f32_e32 v151, v147
	v_sub_f32_e32 v147, v149, v153
	v_exp_f32_e32 v150, v147
	v_sub_f32_e32 v147, v152, v153
	v_exp_f32_e32 v147, v147
	v_add_f32_e32 v149, v151, v150
	v_add_f32_e32 v149, v147, v149
	v_div_scale_f32 v152, s[14:15], v149, v149, 1.0
	v_rcp_f32_e32 v153, v152
	s_waitcnt vmcnt(39)
; #define CMB(f) { const float lo = (w0 * bflo(og[q][0].f) + w1 * bflo(og[q][1].f) + w2 * bflo(og[q][2].f)) * bflo(z.f); const float hi = (w0 * bfhi(og[q][0].f) + w1 * bfhi(og[q][1].f) + w2 * bfhi(og[q][2].f)) * bfhi(z.f); o.f = cvtpk(lo, hi); }
; __device__ __forceinline__ void attnA_unit(LAS unsigned char* lds, const Args& A, int unit) {
;     ...
; #pragma unroll
;         for (int q = 0; q < 4; ++q) {
;             const int e = (it0 + q) * 512 + tid, tl = e >> 3, ch = e & 7, s = c * 1024 + tl;
;             const float M = fmaxf(ls2[q][0], fmaxf(ls2[q][1], ls2[q][2]));
;             float w0 = __builtin_amdgcn_exp2f(ls2[q][0] - M), w1 = __builtin_amdgcn_exp2f(ls2[q][1] - M), w2 = __builtin_amdgcn_exp2f(ls2[q][2] - M);
;             const float wi = 1.0f / (w0 + w1 + w2); w0 *= wi; w1 *= wi; w2 *= wi;
;             const u32x4 z = zv[q]; u32x4 o;
;     ...
;             CMB(x) CMB(y) CMB(z) CMB(w)
;     ...
;             *(u32x4*)(SAZ + (size_t)(b * 8192 + s) * 512 + h * 64 + ch * 8) = o;
	v_lshlrev_b32_e32 v158, 16, v108
	v_fma_f32 v154, -v152, v153, 1.0
	v_fmac_f32_e32 v153, v154, v153
	v_div_scale_f32 v154, vcc, 1.0, v149, 1.0
	v_mul_f32_e32 v156, v154, v153
	v_fma_f32 v157, -v152, v156, v154
	v_fmac_f32_e32 v156, v157, v153
	v_fma_f32 v152, -v152, v156, v154
	v_div_fmas_f32 v152, v152, v153, v156
	v_div_fixup_f32 v152, v152, v149, 1.0
	v_pk_mul_f32 v[150:151], v[150:151], v[152:153] op_sel_hi:[1,0]
	v_lshlrev_b32_e32 v156, 16, v100
	v_and_b32_e32 v157, 0xffff0000, v104
	v_mul_f32_e32 v154, v147, v152
	v_lshlrev_b32_e32 v152, 16, v104
	v_and_b32_e32 v153, 0xffff0000, v100
	v_pk_mul_f32 v[156:157], v[150:151], v[156:157] op_sel:[1,0] op_sel_hi:[0,1]
	v_and_b32_e32 v159, 0xffff0000, v108
	v_pk_fma_f32 v[152:153], v[150:151], v[152:153], v[156:157]
	s_waitcnt vmcnt(38)
	v_lshlrev_b32_e32 v238, 16, v112
	v_and_b32_e32 v239, 0xffff0000, v112
	v_pk_fma_f32 v[152:153], v[154:155], v[158:159], v[152:153] op_sel_hi:[0,1,1]
	v_pk_mul_f32 v[152:153], v[152:153], v[238:239]
	v_lshlrev_b32_e32 v104, 16, v101
	v_cvt_pk_bf16_f32 v100, v152, v153
	v_lshlrev_b32_e32 v152, 16, v105
	v_and_b32_e32 v105, 0xffff0000, v105
	v_and_b32_e32 v153, 0xffff0000, v101
	v_pk_mul_f32 v[104:105], v[150:151], v[104:105] op_sel:[1,0] op_sel_hi:[0,1]
	v_lshlrev_b32_e32 v108, 16, v109
	v_and_b32_e32 v109, 0xffff0000, v109
	v_pk_fma_f32 v[104:105], v[150:151], v[152:153], v[104:105]
	v_lshlrev_b32_e32 v112, 16, v113
	v_and_b32_e32 v113, 0xffff0000, v113
	v_pk_fma_f32 v[104:105], v[154:155], v[108:109], v[104:105] op_sel_hi:[0,1,1]
	v_pk_mul_f32 v[104:105], v[104:105], v[112:113]
	v_lshlrev_b32_e32 v108, 16, v102
	v_and_b32_e32 v109, 0xffff0000, v106
	v_cvt_pk_bf16_f32 v101, v104, v105
	v_lshlrev_b32_e32 v104, 16, v106
	v_and_b32_e32 v105, 0xffff0000, v102
	v_pk_mul_f32 v[108:109], v[150:151], v[108:109] op_sel:[1,0] op_sel_hi:[0,1]
	v_lshlrev_b32_e32 v112, 16, v110
	v_and_b32_e32 v113, 0xffff0000, v110
	v_pk_fma_f32 v[104:105], v[150:151], v[104:105], v[108:109]
	v_lshlrev_b32_e32 v152, 16, v114
	v_and_b32_e32 v153, 0xffff0000, v114
	v_pk_fma_f32 v[104:105], v[154:155], v[112:113], v[104:105] op_sel_hi:[0,1,1]
	v_pk_mul_f32 v[104:105], v[104:105], v[152:153]
	v_lshlrev_b32_e32 v106, 16, v103
	v_cvt_pk_bf16_f32 v102, v104, v105
	v_lshlrev_b32_e32 v104, 16, v107
	v_and_b32_e32 v107, 0xffff0000, v107
	v_and_b32_e32 v105, 0xffff0000, v103
	v_pk_mul_f32 v[106:107], v[150:151], v[106:107] op_sel:[1,0] op_sel_hi:[0,1]
	v_pk_fma_f32 v[104:105], v[150:151], v[104:105], v[106:107]
	v_lshlrev_b32_e32 v106, 16, v111
	v_and_b32_e32 v107, 0xffff0000, v111
	v_pk_fma_f32 v[104:105], v[154:155], v[106:107], v[104:105] op_sel_hi:[0,1,1]
	v_lshlrev_b32_e32 v106, 16, v115
	v_and_b32_e32 v107, 0xffff0000, v115
	v_pk_mul_f32 v[104:105], v[104:105], v[106:107]
	v_and_b32_e32 v109, 0xffff0000, v124
	v_cvt_pk_bf16_f32 v103, v104, v105
	v_add_u32_e32 v104, s12, v146
	v_ashrrev_i32_e32 v105, 31, v104
	v_lshlrev_b64 v[104:105], 10, v[104:105]
	v_lshl_add_u64 v[104:105], v[66:67], 0, v[104:105]
	global_store_dwordx4 v[104:105], v[100:103], off
	s_waitcnt vmcnt(37)
	v_lshlrev_b32_e32 v110, 16, v128
	v_and_b32_e32 v111, 0xffff0000, v128
	v_max3_f32 v102, v155, v240, v241
	v_sub_f32_e32 v100, v155, v102
	v_exp_f32_e32 v101, v100
	v_sub_f32_e32 v100, v240, v102
	v_exp_f32_e32 v100, v100
	v_sub_f32_e32 v102, v241, v102
	v_exp_f32_e32 v103, v102
	v_lshlrev_b32_e32 v112, 16, v129
	v_add_f32_e32 v102, v101, v100
	v_and_b32_e32 v113, 0xffff0000, v129
	v_add_f32_e32 v102, v103, v102
	v_div_scale_f32 v104, s[14:15], v102, v102, 1.0
	v_rcp_f32_e32 v105, v104
	s_nop 0
	v_fma_f32 v106, -v104, v105, 1.0
	v_fmac_f32_e32 v105, v106, v105
	v_div_scale_f32 v106, vcc, 1.0, v102, 1.0
	v_mul_f32_e32 v107, v106, v105
	v_fma_f32 v108, -v104, v107, v106
	v_fmac_f32_e32 v107, v108, v105
	v_fma_f32 v104, -v104, v107, v106
	v_div_fmas_f32 v104, v104, v105, v107
	v_div_fixup_f32 v102, v104, v102, 1.0
	v_mul_f32_e32 v104, v103, v102
	v_pk_mul_f32 v[106:107], v[100:101], v[102:103] op_sel_hi:[1,0]
	v_lshlrev_b32_e32 v102, 16, v116
	v_and_b32_e32 v103, 0xffff0000, v120
	v_lshlrev_b32_e32 v100, 16, v120
	v_and_b32_e32 v101, 0xffff0000, v116
	v_pk_mul_f32 v[102:103], v[106:107], v[102:103] op_sel:[1,0] op_sel_hi:[0,1]
	v_lshlrev_b32_e32 v108, 16, v124
	v_pk_fma_f32 v[100:101], v[106:107], v[100:101], v[102:103]
	v_lshlrev_b32_e32 v102, 16, v121
	v_pk_fma_f32 v[100:101], v[104:105], v[108:109], v[100:101] op_sel_hi:[0,1,1]
	v_lshlrev_b32_e32 v108, 16, v117
	v_and_b32_e32 v109, 0xffff0000, v121
	v_and_b32_e32 v103, 0xffff0000, v117
	v_pk_mul_f32 v[108:109], v[106:107], v[108:109] op_sel:[1,0] op_sel_hi:[0,1]
	v_pk_mul_f32 v[100:101], v[100:101], v[110:111]
	v_lshlrev_b32_e32 v110, 16, v125
	v_and_b32_e32 v111, 0xffff0000, v125
	v_pk_fma_f32 v[102:103], v[106:107], v[102:103], v[108:109]
	v_lshlrev_b32_e32 v108, 16, v118
	v_pk_fma_f32 v[102:103], v[104:105], v[110:111], v[102:103] op_sel_hi:[0,1,1]
	v_pk_mul_f32 v[102:103], v[102:103], v[112:113]
	v_and_b32_e32 v109, 0xffff0000, v122
	v_cvt_pk_bf16_f32 v100, v100, v101
	v_cvt_pk_bf16_f32 v101, v102, v103
	v_lshlrev_b32_e32 v102, 16, v122
	v_and_b32_e32 v103, 0xffff0000, v118
	v_pk_mul_f32 v[108:109], v[106:107], v[108:109] op_sel:[1,0] op_sel_hi:[0,1]
	v_lshlrev_b32_e32 v110, 16, v126
	v_and_b32_e32 v111, 0xffff0000, v126
	v_pk_fma_f32 v[102:103], v[106:107], v[102:103], v[108:109]
	v_lshlrev_b32_e32 v108, 16, v123
	v_pk_fma_f32 v[102:103], v[104:105], v[110:111], v[102:103] op_sel_hi:[0,1,1]
	v_lshlrev_b32_e32 v110, 16, v119
	v_and_b32_e32 v111, 0xffff0000, v123
	v_and_b32_e32 v109, 0xffff0000, v119
	v_pk_mul_f32 v[110:111], v[106:107], v[110:111] op_sel:[1,0] op_sel_hi:[0,1]
	v_pk_fma_f32 v[106:107], v[106:107], v[108:109], v[110:111]
	v_lshlrev_b32_e32 v108, 16, v127
	v_and_b32_e32 v109, 0xffff0000, v127
	v_lshlrev_b32_e32 v112, 16, v130
	v_and_b32_e32 v113, 0xffff0000, v130
	v_pk_fma_f32 v[104:105], v[104:105], v[108:109], v[106:107] op_sel_hi:[0,1,1]
	v_lshlrev_b32_e32 v106, 16, v131
	v_and_b32_e32 v107, 0xffff0000, v131
	v_pk_mul_f32 v[102:103], v[102:103], v[112:113]
	v_pk_mul_f32 v[104:105], v[104:105], v[106:107]
	v_cvt_pk_bf16_f32 v102, v102, v103
	v_cvt_pk_bf16_f32 v103, v104, v105
	v_add_u32_e32 v104, s12, v148
	v_ashrrev_i32_e32 v105, 31, v104
	v_lshlrev_b64 v[104:105], 10, v[104:105]
	v_lshl_add_u64 v[104:105], v[66:67], 0, v[104:105]
	global_store_dwordx4 v[104:105], v[100:103], off
	v_and_b32_e32 v109, 0xffff0000, v140
	s_waitcnt vmcnt(36)
; #define CMB(f) { const float lo = (w0 * bflo(og[q][0].f) + w1 * bflo(og[q][1].f) + w2 * bflo(og[q][2].f)) * bflo(z.f); const float hi = (w0 * bfhi(og[q][0].f) + w1 * bfhi(og[q][1].f) + w2 * bfhi(og[q][2].f)) * bfhi(z.f); o.f = cvtpk(lo, hi); }
; __device__ __forceinline__ void attnA_unit(LAS unsigned char* lds, const Args& A, int unit) {
;     ...
;         for (int q = 0; q < 4; ++q) {
;             const int e = (it0 + q) * 512 + tid, tl = e >> 3, ch = e & 7, s = c * 1024 + tl;
;             const float M = fmaxf(ls2[q][0], fmaxf(ls2[q][1], ls2[q][2]));
;             float w0 = __builtin_amdgcn_exp2f(ls2[q][0] - M), w1 = __builtin_amdgcn_exp2f(ls2[q][1] - M), w2 = __builtin_amdgcn_exp2f(ls2[q][2] - M);
;             const float wi = 1.0f / (w0 + w1 + w2); w0 *= wi; w1 *= wi; w2 *= wi;
;             const u32x4 z = zv[q]; u32x4 o;
;     ...
;             CMB(x) CMB(y) CMB(z) CMB(w)
;     ...
;             *(u32x4*)(SAZ + (size_t)(b * 8192 + s) * 512 + h * 64 + ch * 8) = o;
	v_lshlrev_b32_e32 v110, 16, v190
	v_max3_f32 v102, v243, v244, v245
	v_sub_f32_e32 v100, v243, v102
	v_exp_f32_e32 v101, v100
	v_sub_f32_e32 v100, v244, v102
	v_exp_f32_e32 v100, v100
	v_sub_f32_e32 v102, v245, v102
	v_exp_f32_e32 v103, v102
	v_and_b32_e32 v111, 0xffff0000, v190
	v_add_f32_e32 v102, v101, v100
	v_lshlrev_b32_e32 v112, 16, v191
	v_add_f32_e32 v102, v103, v102
	v_div_scale_f32 v104, s[14:15], v102, v102, 1.0
	v_rcp_f32_e32 v105, v104
	v_and_b32_e32 v113, 0xffff0000, v191
	v_fma_f32 v106, -v104, v105, 1.0
	v_fmac_f32_e32 v105, v106, v105
	v_div_scale_f32 v106, vcc, 1.0, v102, 1.0
	v_mul_f32_e32 v107, v106, v105
	v_fma_f32 v108, -v104, v107, v106
	v_fmac_f32_e32 v107, v108, v105
	v_fma_f32 v104, -v104, v107, v106
	v_div_fmas_f32 v104, v104, v105, v107
	v_div_fixup_f32 v102, v104, v102, 1.0
	v_mul_f32_e32 v104, v103, v102
	v_pk_mul_f32 v[106:107], v[100:101], v[102:103] op_sel_hi:[1,0]
	v_lshlrev_b32_e32 v102, 16, v132
	v_and_b32_e32 v103, 0xffff0000, v136
	v_lshlrev_b32_e32 v100, 16, v136
	v_and_b32_e32 v101, 0xffff0000, v132
	v_pk_mul_f32 v[102:103], v[106:107], v[102:103] op_sel:[1,0] op_sel_hi:[0,1]
	v_lshlrev_b32_e32 v108, 16, v140
	v_pk_fma_f32 v[100:101], v[106:107], v[100:101], v[102:103]
	v_lshlrev_b32_e32 v102, 16, v137
	v_pk_fma_f32 v[100:101], v[104:105], v[108:109], v[100:101] op_sel_hi:[0,1,1]
	v_lshlrev_b32_e32 v108, 16, v133
	v_and_b32_e32 v109, 0xffff0000, v137
	v_and_b32_e32 v103, 0xffff0000, v133
	v_pk_mul_f32 v[108:109], v[106:107], v[108:109] op_sel:[1,0] op_sel_hi:[0,1]
	v_pk_mul_f32 v[100:101], v[100:101], v[110:111]
	v_lshlrev_b32_e32 v110, 16, v141
	v_and_b32_e32 v111, 0xffff0000, v141
	v_pk_fma_f32 v[102:103], v[106:107], v[102:103], v[108:109]
	v_lshlrev_b32_e32 v108, 16, v134
	v_pk_fma_f32 v[102:103], v[104:105], v[110:111], v[102:103] op_sel_hi:[0,1,1]
	v_pk_mul_f32 v[102:103], v[102:103], v[112:113]
	v_and_b32_e32 v109, 0xffff0000, v138
	v_cvt_pk_bf16_f32 v100, v100, v101
	v_cvt_pk_bf16_f32 v101, v102, v103
	v_lshlrev_b32_e32 v102, 16, v138
	v_and_b32_e32 v103, 0xffff0000, v134
	v_pk_mul_f32 v[108:109], v[106:107], v[108:109] op_sel:[1,0] op_sel_hi:[0,1]
	v_lshlrev_b32_e32 v110, 16, v142
	v_and_b32_e32 v111, 0xffff0000, v142
	v_pk_fma_f32 v[102:103], v[106:107], v[102:103], v[108:109]
	v_lshlrev_b32_e32 v108, 16, v139
	v_pk_fma_f32 v[102:103], v[104:105], v[110:111], v[102:103] op_sel_hi:[0,1,1]
	v_lshlrev_b32_e32 v110, 16, v135
	v_and_b32_e32 v111, 0xffff0000, v139
	v_and_b32_e32 v109, 0xffff0000, v135
	v_pk_mul_f32 v[110:111], v[106:107], v[110:111] op_sel:[1,0] op_sel_hi:[0,1]
	v_pk_fma_f32 v[106:107], v[106:107], v[108:109], v[110:111]
	v_lshlrev_b32_e32 v108, 16, v143
	v_and_b32_e32 v109, 0xffff0000, v143
	v_lshlrev_b32_e32 v112, 16, v192
	v_and_b32_e32 v113, 0xffff0000, v192
	v_pk_fma_f32 v[104:105], v[104:105], v[108:109], v[106:107] op_sel_hi:[0,1,1]
	v_lshlrev_b32_e32 v106, 16, v193
	v_and_b32_e32 v107, 0xffff0000, v193
	v_pk_mul_f32 v[102:103], v[102:103], v[112:113]
	v_pk_mul_f32 v[104:105], v[104:105], v[106:107]
	v_cvt_pk_bf16_f32 v102, v102, v103
	v_cvt_pk_bf16_f32 v103, v104, v105
	v_add_u32_e32 v104, s12, v242
	v_ashrrev_i32_e32 v105, 31, v104
	v_lshlrev_b64 v[104:105], 10, v[104:105]
	v_lshl_add_u64 v[104:105], v[66:67], 0, v[104:105]
	global_store_dwordx4 v[104:105], v[100:103], off
	v_and_b32_e32 v109, 0xffff0000, v202
	s_waitcnt vmcnt(35)
	v_lshlrev_b32_e32 v110, 16, v206
	v_max3_f32 v102, v247, v248, v249
	v_sub_f32_e32 v100, v247, v102
	v_exp_f32_e32 v101, v100
	v_sub_f32_e32 v100, v248, v102
	v_exp_f32_e32 v100, v100
	v_sub_f32_e32 v102, v249, v102
	v_exp_f32_e32 v103, v102
	v_and_b32_e32 v111, 0xffff0000, v206
	v_add_f32_e32 v102, v101, v100
	v_lshlrev_b32_e32 v112, 16, v207
	v_add_f32_e32 v102, v103, v102
	v_div_scale_f32 v104, s[14:15], v102, v102, 1.0
	v_rcp_f32_e32 v105, v104
	v_and_b32_e32 v113, 0xffff0000, v207
	v_fma_f32 v106, -v104, v105, 1.0
	v_fmac_f32_e32 v105, v106, v105
	v_div_scale_f32 v106, vcc, 1.0, v102, 1.0
	v_mul_f32_e32 v107, v106, v105
	v_fma_f32 v108, -v104, v107, v106
	v_fmac_f32_e32 v107, v108, v105
	v_fma_f32 v104, -v104, v107, v106
	v_div_fmas_f32 v104, v104, v105, v107
	v_div_fixup_f32 v102, v104, v102, 1.0
	v_mul_f32_e32 v104, v103, v102
	v_pk_mul_f32 v[106:107], v[100:101], v[102:103] op_sel_hi:[1,0]
	v_lshlrev_b32_e32 v102, 16, v194
	v_and_b32_e32 v103, 0xffff0000, v198
	v_lshlrev_b32_e32 v100, 16, v198
	v_and_b32_e32 v101, 0xffff0000, v194
	v_pk_mul_f32 v[102:103], v[106:107], v[102:103] op_sel:[1,0] op_sel_hi:[0,1]
	v_lshlrev_b32_e32 v108, 16, v202
	v_pk_fma_f32 v[100:101], v[106:107], v[100:101], v[102:103]
	v_lshlrev_b32_e32 v102, 16, v199
	v_pk_fma_f32 v[100:101], v[104:105], v[108:109], v[100:101] op_sel_hi:[0,1,1]
	v_lshlrev_b32_e32 v108, 16, v195
	v_and_b32_e32 v109, 0xffff0000, v199
	v_and_b32_e32 v103, 0xffff0000, v195
	v_pk_mul_f32 v[108:109], v[106:107], v[108:109] op_sel:[1,0] op_sel_hi:[0,1]
	v_pk_mul_f32 v[100:101], v[100:101], v[110:111]
	v_lshlrev_b32_e32 v110, 16, v203
	v_and_b32_e32 v111, 0xffff0000, v203
	v_pk_fma_f32 v[102:103], v[106:107], v[102:103], v[108:109]
	v_lshlrev_b32_e32 v108, 16, v196
	v_pk_fma_f32 v[102:103], v[104:105], v[110:111], v[102:103] op_sel_hi:[0,1,1]
	v_pk_mul_f32 v[102:103], v[102:103], v[112:113]
	v_and_b32_e32 v109, 0xffff0000, v200
	v_cvt_pk_bf16_f32 v100, v100, v101
	v_cvt_pk_bf16_f32 v101, v102, v103
	v_lshlrev_b32_e32 v102, 16, v200
	v_and_b32_e32 v103, 0xffff0000, v196
	v_pk_mul_f32 v[108:109], v[106:107], v[108:109] op_sel:[1,0] op_sel_hi:[0,1]
	v_lshlrev_b32_e32 v110, 16, v204
	v_and_b32_e32 v111, 0xffff0000, v204
	v_pk_fma_f32 v[102:103], v[106:107], v[102:103], v[108:109]
; __device__ __forceinline__ void attnA_unit(LAS unsigned char* lds, const Args& A, int unit) {
;     ...
;     for (int it0 = 0; it0 < 16; it0 += 4) {
;         float ls2[4][3]; u32x4 og[4][3], zv[4];
; #pragma unroll
;         for (int q = 0; q < 4; ++q) {
;             const int e = (it0 + q) * 512 + tid, tl = e >> 3, ch = e & 7, s = c * 1024 + tl;
; #pragma unroll
;             for (int g = 0; g < 3; ++g) { const int lg = 2 * g, p = ((s & ((1 << lg) - 1)) << (13 - lg)) | (s >> lg);
;                 ls2[q][g] = LSE[(size_t)((g * 4 + b) * 8 + h) * 8192 + p];
;                 og[q][g] = *(const u32x4*)((const bf16*)(A.ws + WS_QA) + ((size_t)((b * 3 + g) * 8 + h) * 8192 + p) * 64 + ch * 8); }
;             zv[q] = *(const u32x4*)(SAZ + (size_t)(b * 8192 + s) * 512 + h * 64 + ch * 8);
;         }
	v_lshlrev_b32_e32 v108, 16, v201
	v_pk_fma_f32 v[102:103], v[104:105], v[110:111], v[102:103] op_sel_hi:[0,1,1]
	v_lshlrev_b32_e32 v110, 16, v197
	v_and_b32_e32 v111, 0xffff0000, v201
	v_and_b32_e32 v109, 0xffff0000, v197
	v_pk_mul_f32 v[110:111], v[106:107], v[110:111] op_sel:[1,0] op_sel_hi:[0,1]
	v_pk_fma_f32 v[106:107], v[106:107], v[108:109], v[110:111]
	v_lshlrev_b32_e32 v108, 16, v205
	v_and_b32_e32 v109, 0xffff0000, v205
	v_lshlrev_b32_e32 v112, 16, v208
	v_and_b32_e32 v113, 0xffff0000, v208
	v_pk_fma_f32 v[104:105], v[104:105], v[108:109], v[106:107] op_sel_hi:[0,1,1]
	v_lshlrev_b32_e32 v106, 16, v209
	v_and_b32_e32 v107, 0xffff0000, v209
	v_pk_mul_f32 v[102:103], v[102:103], v[112:113]
	v_pk_mul_f32 v[104:105], v[104:105], v[106:107]
	v_cvt_pk_bf16_f32 v102, v102, v103
	v_cvt_pk_bf16_f32 v103, v104, v105
	v_add_u32_e32 v104, s12, v246
	v_ashrrev_i32_e32 v105, 31, v104
	v_lshlrev_b64 v[104:105], 10, v[104:105]
	v_lshl_add_u64 v[104:105], v[66:67], 0, v[104:105]
	global_store_dwordx4 v[104:105], v[100:103], off
	v_add_u32_e32 v116, 0x200, v145
	v_add_u32_e32 v132, 0x400, v145
	v_add_u32_e32 v194, 0x600, v145
	v_ashrrev_i32_e32 v146, 3, v145
	v_ashrrev_i32_e32 v148, 3, v116
	v_ashrrev_i32_e32 v242, 3, v132
	v_ashrrev_i32_e32 v246, 3, v194
	v_add_u32_e32 v112, s10, v146
	v_add_u32_e32 v128, s10, v148
	v_add_u32_e32 v190, s10, v242
	v_add_u32_e32 v206, s10, v246
	v_lshlrev_b32_e32 v104, 11, v146
	v_ashrrev_i32_e32 v105, 2, v112
	v_lshlrev_b32_e32 v120, 11, v148
	v_ashrrev_i32_e32 v121, 2, v128
	v_lshlrev_b32_e32 v124, 9, v148
	v_ashrrev_i32_e32 v125, 4, v128
	v_lshlrev_b32_e32 v136, 11, v242
	v_ashrrev_i32_e32 v137, 2, v190
	v_lshlrev_b32_e32 v140, 9, v242
	v_ashrrev_i32_e32 v141, 4, v190
	v_lshlrev_b32_e32 v198, 11, v246
	v_ashrrev_i32_e32 v199, 2, v206
	v_lshlrev_b32_e32 v202, 9, v246
	v_ashrrev_i32_e32 v203, 4, v206
	v_and_or_b32 v104, v104, s89, v105
	v_lshlrev_b32_e32 v108, 9, v146
	v_ashrrev_i32_e32 v109, 4, v112
	v_and_or_b32 v120, v120, s89, v121
	v_and_or_b32 v124, v124, s50, v125
	v_and_or_b32 v136, v136, s89, v137
	v_and_or_b32 v140, v140, s50, v141
	v_and_or_b32 v198, v198, s89, v199
	v_and_or_b32 v202, v202, s50, v203
	v_ashrrev_i32_e32 v105, 31, v104
	v_and_or_b32 v108, v108, s50, v109
	v_ashrrev_i32_e32 v121, 31, v120
	v_ashrrev_i32_e32 v125, 31, v124
	v_ashrrev_i32_e32 v137, 31, v136
	v_ashrrev_i32_e32 v141, 31, v140
	v_ashrrev_i32_e32 v199, 31, v198
	v_ashrrev_i32_e32 v203, 31, v202
	v_ashrrev_i32_e32 v113, 31, v112
	v_lshl_add_u64 v[106:107], v[104:105], 2, s[6:7]
	v_lshlrev_b64 v[104:105], 7, v[104:105]
	v_ashrrev_i32_e32 v109, 31, v108
	v_ashrrev_i32_e32 v129, 31, v128
	v_lshl_add_u64 v[122:123], v[120:121], 2, s[6:7]
	v_lshlrev_b64 v[120:121], 7, v[120:121]
	v_lshl_add_u64 v[126:127], v[124:125], 2, s[8:9]
	v_lshlrev_b64 v[124:125], 7, v[124:125]
	v_ashrrev_i32_e32 v191, 31, v190
	v_lshl_add_u64 v[138:139], v[136:137], 2, s[6:7]
	v_lshlrev_b64 v[136:137], 7, v[136:137]
	v_lshl_add_u64 v[142:143], v[140:141], 2, s[8:9]
	v_lshlrev_b64 v[140:141], 7, v[140:141]
	v_ashrrev_i32_e32 v207, 31, v206
	v_lshl_add_u64 v[200:201], v[198:199], 2, s[6:7]
	v_lshlrev_b64 v[198:199], 7, v[198:199]
	v_lshl_add_u64 v[204:205], v[202:203], 2, s[8:9]
	v_lshlrev_b64 v[202:203], 7, v[202:203]
	v_lshl_add_u64 v[100:101], v[112:113], 2, s[4:5]
	v_lshl_add_u64 v[104:105], v[70:71], 0, v[104:105]
	v_lshl_add_u64 v[110:111], v[108:109], 2, s[8:9]
	v_lshl_add_u64 v[116:117], v[128:129], 2, s[4:5]
	v_lshl_add_u64 v[120:121], v[70:71], 0, v[120:121]
	v_lshl_add_u64 v[124:125], v[72:73], 0, v[124:125]
	v_lshl_add_u64 v[132:133], v[190:191], 2, s[4:5]
	v_lshl_add_u64 v[136:137], v[70:71], 0, v[136:137]
	v_lshl_add_u64 v[140:141], v[72:73], 0, v[140:141]
	v_lshl_add_u64 v[194:195], v[206:207], 2, s[4:5]
	v_lshl_add_u64 v[198:199], v[70:71], 0, v[198:199]
	v_lshl_add_u64 v[202:203], v[72:73], 0, v[202:203]
	global_load_dword v147, v[100:101], off
	global_load_dword v152, v[110:111], off
	global_load_dword v149, v[106:107], off
	global_load_dword v155, v[116:117], off
	global_load_dword v240, v[122:123], off
	global_load_dword v243, v[132:133], off
	global_load_dword v241, v[126:127], off
	global_load_dword v244, v[138:139], off
	global_load_dword v247, v[194:195], off
	global_load_dword v245, v[142:143], off
	global_load_dword v248, v[200:201], off
	global_load_dword v249, v[204:205], off
	v_lshlrev_b64 v[108:109], 7, v[108:109]
	global_load_dwordx4 v[202:205], v[202:203], off
	v_lshl_add_u64 v[108:109], v[72:73], 0, v[108:109]
	global_load_dwordx4 v[198:201], v[198:199], off
	v_lshlrev_b64 v[132:133], 7, v[190:191]
	global_load_dwordx4 v[140:143], v[140:141], off
	v_lshl_add_u64 v[132:133], v[68:69], 0, v[132:133]
	global_load_dwordx4 v[136:139], v[136:137], off
	v_add_u32_e32 v190, s11, v190
	global_load_dwordx4 v[124:127], v[124:125], off
	v_ashrrev_i32_e32 v191, 31, v190
	global_load_dwordx4 v[120:123], v[120:121], off
	v_lshlrev_b64 v[116:117], 7, v[128:129]
	global_load_dwordx4 v[104:107], v[104:105], off
	v_lshlrev_b64 v[100:101], 7, v[112:113]
	v_lshl_add_u64 v[100:101], v[68:69], 0, v[100:101]
	v_add_u32_e32 v112, s11, v112
	global_load_dwordx4 v[100:103], v[100:101], off
	v_ashrrev_i32_e32 v113, 31, v112
	v_lshlrev_b64 v[112:113], 10, v[112:113]
	global_load_dwordx4 v[108:111], v[108:109], off
	v_lshl_add_u64 v[112:113], v[64:65], 0, v[112:113]
	global_load_dwordx4 v[112:115], v[112:113], off
	v_lshl_add_u64 v[116:117], v[68:69], 0, v[116:117]
	global_load_dwordx4 v[116:119], v[116:117], off
	v_add_u32_e32 v128, s11, v128
	v_ashrrev_i32_e32 v129, 31, v128
	v_lshlrev_b64 v[128:129], 10, v[128:129]
	v_lshl_add_u64 v[128:129], v[64:65], 0, v[128:129]
	global_load_dwordx4 v[128:131], v[128:129], off
	v_lshlrev_b64 v[190:191], 10, v[190:191]
	global_load_dwordx4 v[132:135], v[132:133], off
	v_lshl_add_u64 v[190:191], v[64:65], 0, v[190:191]
	global_load_dwordx4 v[190:193], v[190:191], off
	v_lshlrev_b64 v[194:195], 7, v[206:207]
	v_add_u32_e32 v206, s11, v206
	v_ashrrev_i32_e32 v207, 31, v206
	v_lshlrev_b64 v[206:207], 10, v[206:207]
	v_lshl_add_u64 v[194:195], v[68:69], 0, v[194:195]
	v_lshl_add_u64 v[206:207], v[64:65], 0, v[206:207]
	global_load_dwordx4 v[194:197], v[194:195], off
	global_load_dwordx4 v[206:209], v[206:207], off
	v_add_u32_e32 v145, 0x800, v145
	s_waitcnt vmcnt(57)
; #define CMB(f) { const float lo = (w0 * bflo(og[q][0].f) + w1 * bflo(og[q][1].f) + w2 * bflo(og[q][2].f)) * bflo(z.f); const float hi = (w0 * bfhi(og[q][0].f) + w1 * bfhi(og[q][1].f) + w2 * bfhi(og[q][2].f)) * bfhi(z.f); o.f = cvtpk(lo, hi); }
; __device__ __forceinline__ void attnA_unit(LAS unsigned char* lds, const Args& A, int unit) {
;     ...
;         for (int q = 0; q < 4; ++q) {
;             const int e = (it0 + q) * 512 + tid, tl = e >> 3, ch = e & 7, s = c * 1024 + tl;
;             const float M = fmaxf(ls2[q][0], fmaxf(ls2[q][1], ls2[q][2]));
;             float w0 = __builtin_amdgcn_exp2f(ls2[q][0] - M), w1 = __builtin_amdgcn_exp2f(ls2[q][1] - M), w2 = __builtin_amdgcn_exp2f(ls2[q][2] - M);
;             const float wi = 1.0f / (w0 + w1 + w2); w0 *= wi; w1 *= wi; w2 *= wi;
;             const u32x4 z = zv[q]; u32x4 o;
;     ...
;             CMB(x) CMB(y) CMB(z) CMB(w)
;     ...
;             *(u32x4*)(SAZ + (size_t)(b * 8192 + s) * 512 + h * 64 + ch * 8) = o;
	v_max3_f32 v81, v75, v77, v80
	v_sub_f32_e32 v75, v75, v81
	v_exp_f32_e32 v79, v75
	v_sub_f32_e32 v75, v77, v81
	v_exp_f32_e32 v78, v75
	v_sub_f32_e32 v75, v80, v81
	v_exp_f32_e32 v75, v75
	v_add_f32_e32 v77, v79, v78
	v_add_f32_e32 v77, v75, v77
	v_div_scale_f32 v80, s[14:15], v77, v77, 1.0
	v_rcp_f32_e32 v81, v80
	s_waitcnt vmcnt(39)
	v_lshlrev_b32_e32 v86, 16, v8
	v_fma_f32 v82, -v80, v81, 1.0
	v_fmac_f32_e32 v81, v82, v81
	v_div_scale_f32 v82, vcc, 1.0, v77, 1.0
	v_mul_f32_e32 v84, v82, v81
	v_fma_f32 v85, -v80, v84, v82
	v_fmac_f32_e32 v84, v85, v81
	v_fma_f32 v80, -v80, v84, v82
	v_div_fmas_f32 v80, v80, v81, v84
	v_div_fixup_f32 v80, v80, v77, 1.0
	v_pk_mul_f32 v[78:79], v[78:79], v[80:81] op_sel_hi:[1,0]
	v_lshlrev_b32_e32 v84, 16, v0
	v_and_b32_e32 v85, 0xffff0000, v4
	v_mul_f32_e32 v82, v75, v80
	v_lshlrev_b32_e32 v80, 16, v4
	v_and_b32_e32 v81, 0xffff0000, v0
	v_pk_mul_f32 v[84:85], v[78:79], v[84:85] op_sel:[1,0] op_sel_hi:[0,1]
	v_and_b32_e32 v87, 0xffff0000, v8
	v_pk_fma_f32 v[80:81], v[78:79], v[80:81], v[84:85]
	s_waitcnt vmcnt(38)
	v_lshlrev_b32_e32 v88, 16, v12
	v_and_b32_e32 v89, 0xffff0000, v12
	v_pk_fma_f32 v[80:81], v[82:83], v[86:87], v[80:81] op_sel_hi:[0,1,1]
	v_pk_mul_f32 v[80:81], v[80:81], v[88:89]
	v_lshlrev_b32_e32 v4, 16, v1
	v_cvt_pk_bf16_f32 v0, v80, v81
	v_lshlrev_b32_e32 v80, 16, v5
	v_and_b32_e32 v5, 0xffff0000, v5
	v_and_b32_e32 v81, 0xffff0000, v1
	v_pk_mul_f32 v[4:5], v[78:79], v[4:5] op_sel:[1,0] op_sel_hi:[0,1]
	v_lshlrev_b32_e32 v8, 16, v9
	v_and_b32_e32 v9, 0xffff0000, v9
	v_pk_fma_f32 v[4:5], v[78:79], v[80:81], v[4:5]
	v_lshlrev_b32_e32 v12, 16, v13
	v_and_b32_e32 v13, 0xffff0000, v13
	v_pk_fma_f32 v[4:5], v[82:83], v[8:9], v[4:5] op_sel_hi:[0,1,1]
	v_pk_mul_f32 v[4:5], v[4:5], v[12:13]
	v_lshlrev_b32_e32 v8, 16, v2
	v_and_b32_e32 v9, 0xffff0000, v6
	v_cvt_pk_bf16_f32 v1, v4, v5
	v_lshlrev_b32_e32 v4, 16, v6
	v_and_b32_e32 v5, 0xffff0000, v2
	v_pk_mul_f32 v[8:9], v[78:79], v[8:9] op_sel:[1,0] op_sel_hi:[0,1]
	v_lshlrev_b32_e32 v12, 16, v10
	v_and_b32_e32 v13, 0xffff0000, v10
	v_pk_fma_f32 v[4:5], v[78:79], v[4:5], v[8:9]
	v_lshlrev_b32_e32 v80, 16, v14
	v_and_b32_e32 v81, 0xffff0000, v14
	v_pk_fma_f32 v[4:5], v[82:83], v[12:13], v[4:5] op_sel_hi:[0,1,1]
	v_pk_mul_f32 v[4:5], v[4:5], v[80:81]
	v_lshlrev_b32_e32 v6, 16, v3
	v_cvt_pk_bf16_f32 v2, v4, v5
	v_lshlrev_b32_e32 v4, 16, v7
	v_and_b32_e32 v7, 0xffff0000, v7
	v_and_b32_e32 v5, 0xffff0000, v3
	v_pk_mul_f32 v[6:7], v[78:79], v[6:7] op_sel:[1,0] op_sel_hi:[0,1]
	v_pk_fma_f32 v[4:5], v[78:79], v[4:5], v[6:7]
	v_lshlrev_b32_e32 v6, 16, v11
	v_and_b32_e32 v7, 0xffff0000, v11
	v_pk_fma_f32 v[4:5], v[82:83], v[6:7], v[4:5] op_sel_hi:[0,1,1]
	v_lshlrev_b32_e32 v6, 16, v15
	v_and_b32_e32 v7, 0xffff0000, v15
	v_pk_mul_f32 v[4:5], v[4:5], v[6:7]
	v_and_b32_e32 v9, 0xffff0000, v24
	v_cvt_pk_bf16_f32 v3, v4, v5
	v_add_u32_e32 v4, s12, v74
	v_ashrrev_i32_e32 v5, 31, v4
	v_lshlrev_b64 v[4:5], 10, v[4:5]
	v_lshl_add_u64 v[4:5], v[66:67], 0, v[4:5]
	global_store_dwordx4 v[4:5], v[0:3], off
	s_waitcnt vmcnt(37)
	v_lshlrev_b32_e32 v10, 16, v28
	v_and_b32_e32 v11, 0xffff0000, v28
	v_max3_f32 v2, v83, v90, v91
	v_sub_f32_e32 v0, v83, v2
	v_exp_f32_e32 v1, v0
	v_sub_f32_e32 v0, v90, v2
	v_exp_f32_e32 v0, v0
	v_sub_f32_e32 v2, v91, v2
	v_exp_f32_e32 v3, v2
	v_lshlrev_b32_e32 v12, 16, v29
	v_add_f32_e32 v2, v1, v0
	v_and_b32_e32 v13, 0xffff0000, v29
	v_add_f32_e32 v2, v3, v2
	v_div_scale_f32 v4, s[14:15], v2, v2, 1.0
	v_rcp_f32_e32 v5, v4
	s_nop 0
	v_fma_f32 v6, -v4, v5, 1.0
	v_fmac_f32_e32 v5, v6, v5
	v_div_scale_f32 v6, vcc, 1.0, v2, 1.0
	v_mul_f32_e32 v7, v6, v5
	v_fma_f32 v8, -v4, v7, v6
	v_fmac_f32_e32 v7, v8, v5
	v_fma_f32 v4, -v4, v7, v6
	v_div_fmas_f32 v4, v4, v5, v7
	v_div_fixup_f32 v2, v4, v2, 1.0
	v_mul_f32_e32 v4, v3, v2
	v_pk_mul_f32 v[6:7], v[0:1], v[2:3] op_sel_hi:[1,0]
	v_lshlrev_b32_e32 v2, 16, v16
	v_and_b32_e32 v3, 0xffff0000, v20
	v_lshlrev_b32_e32 v0, 16, v20
	v_and_b32_e32 v1, 0xffff0000, v16
	v_pk_mul_f32 v[2:3], v[6:7], v[2:3] op_sel:[1,0] op_sel_hi:[0,1]
	v_lshlrev_b32_e32 v8, 16, v24
	v_pk_fma_f32 v[0:1], v[6:7], v[0:1], v[2:3]
	v_lshlrev_b32_e32 v2, 16, v21
	v_pk_fma_f32 v[0:1], v[4:5], v[8:9], v[0:1] op_sel_hi:[0,1,1]
	v_lshlrev_b32_e32 v8, 16, v17
	v_and_b32_e32 v9, 0xffff0000, v21
	v_and_b32_e32 v3, 0xffff0000, v17
	v_pk_mul_f32 v[8:9], v[6:7], v[8:9] op_sel:[1,0] op_sel_hi:[0,1]
	v_pk_mul_f32 v[0:1], v[0:1], v[10:11]
	v_lshlrev_b32_e32 v10, 16, v25
	v_and_b32_e32 v11, 0xffff0000, v25
	v_pk_fma_f32 v[2:3], v[6:7], v[2:3], v[8:9]
	v_lshlrev_b32_e32 v8, 16, v18
	v_pk_fma_f32 v[2:3], v[4:5], v[10:11], v[2:3] op_sel_hi:[0,1,1]
	v_pk_mul_f32 v[2:3], v[2:3], v[12:13]
	v_and_b32_e32 v9, 0xffff0000, v22
	v_cvt_pk_bf16_f32 v0, v0, v1
	v_cvt_pk_bf16_f32 v1, v2, v3
	v_lshlrev_b32_e32 v2, 16, v22
	v_and_b32_e32 v3, 0xffff0000, v18
	v_pk_mul_f32 v[8:9], v[6:7], v[8:9] op_sel:[1,0] op_sel_hi:[0,1]
	v_lshlrev_b32_e32 v10, 16, v26
	v_and_b32_e32 v11, 0xffff0000, v26
	v_pk_fma_f32 v[2:3], v[6:7], v[2:3], v[8:9]
	v_lshlrev_b32_e32 v8, 16, v23
	v_pk_fma_f32 v[2:3], v[4:5], v[10:11], v[2:3] op_sel_hi:[0,1,1]
	v_lshlrev_b32_e32 v10, 16, v19
	v_and_b32_e32 v11, 0xffff0000, v23
	v_and_b32_e32 v9, 0xffff0000, v19
	v_pk_mul_f32 v[10:11], v[6:7], v[10:11] op_sel:[1,0] op_sel_hi:[0,1]
	v_pk_fma_f32 v[6:7], v[6:7], v[8:9], v[10:11]
	v_lshlrev_b32_e32 v8, 16, v27
	v_and_b32_e32 v9, 0xffff0000, v27
	v_lshlrev_b32_e32 v12, 16, v30
	v_and_b32_e32 v13, 0xffff0000, v30
	v_pk_fma_f32 v[4:5], v[4:5], v[8:9], v[6:7] op_sel_hi:[0,1,1]
	v_lshlrev_b32_e32 v6, 16, v31
	v_and_b32_e32 v7, 0xffff0000, v31
	v_pk_mul_f32 v[2:3], v[2:3], v[12:13]
	v_pk_mul_f32 v[4:5], v[4:5], v[6:7]
	v_cvt_pk_bf16_f32 v2, v2, v3
	v_cvt_pk_bf16_f32 v3, v4, v5
	v_add_u32_e32 v4, s12, v76
	v_ashrrev_i32_e32 v5, 31, v4
	v_lshlrev_b64 v[4:5], 10, v[4:5]
	v_lshl_add_u64 v[4:5], v[66:67], 0, v[4:5]
	global_store_dwordx4 v[4:5], v[0:3], off
	v_and_b32_e32 v9, 0xffff0000, v40
	s_waitcnt vmcnt(36)
; #define CMB(f) { const float lo = (w0 * bflo(og[q][0].f) + w1 * bflo(og[q][1].f) + w2 * bflo(og[q][2].f)) * bflo(z.f); const float hi = (w0 * bfhi(og[q][0].f) + w1 * bfhi(og[q][1].f) + w2 * bfhi(og[q][2].f)) * bfhi(z.f); o.f = cvtpk(lo, hi); }
; __device__ __forceinline__ void attnA_unit(LAS unsigned char* lds, const Args& A, int unit) {
;     ...
;         for (int q = 0; q < 4; ++q) {
;             const int e = (it0 + q) * 512 + tid, tl = e >> 3, ch = e & 7, s = c * 1024 + tl;
;             const float M = fmaxf(ls2[q][0], fmaxf(ls2[q][1], ls2[q][2]));
;             float w0 = __builtin_amdgcn_exp2f(ls2[q][0] - M), w1 = __builtin_amdgcn_exp2f(ls2[q][1] - M), w2 = __builtin_amdgcn_exp2f(ls2[q][2] - M);
;             const float wi = 1.0f / (w0 + w1 + w2); w0 *= wi; w1 *= wi; w2 *= wi;
;             const u32x4 z = zv[q]; u32x4 o;
;     ...
;             CMB(x) CMB(y) CMB(z) CMB(w)
;     ...
;             *(u32x4*)(SAZ + (size_t)(b * 8192 + s) * 512 + h * 64 + ch * 8) = o;
	v_lshlrev_b32_e32 v10, 16, v44
	v_max3_f32 v2, v93, v94, v95
	v_sub_f32_e32 v0, v93, v2
	v_exp_f32_e32 v1, v0
	v_sub_f32_e32 v0, v94, v2
	v_exp_f32_e32 v0, v0
	v_sub_f32_e32 v2, v95, v2
	v_exp_f32_e32 v3, v2
	v_and_b32_e32 v11, 0xffff0000, v44
	v_add_f32_e32 v2, v1, v0
	v_lshlrev_b32_e32 v12, 16, v45
	v_add_f32_e32 v2, v3, v2
	v_div_scale_f32 v4, s[14:15], v2, v2, 1.0
	v_rcp_f32_e32 v5, v4
	v_and_b32_e32 v13, 0xffff0000, v45
	v_fma_f32 v6, -v4, v5, 1.0
	v_fmac_f32_e32 v5, v6, v5
	v_div_scale_f32 v6, vcc, 1.0, v2, 1.0
	v_mul_f32_e32 v7, v6, v5
	v_fma_f32 v8, -v4, v7, v6
	v_fmac_f32_e32 v7, v8, v5
	v_fma_f32 v4, -v4, v7, v6
	v_div_fmas_f32 v4, v4, v5, v7
	v_div_fixup_f32 v2, v4, v2, 1.0
	v_mul_f32_e32 v4, v3, v2
	v_pk_mul_f32 v[6:7], v[0:1], v[2:3] op_sel_hi:[1,0]
	v_lshlrev_b32_e32 v2, 16, v32
	v_and_b32_e32 v3, 0xffff0000, v36
	v_lshlrev_b32_e32 v0, 16, v36
	v_and_b32_e32 v1, 0xffff0000, v32
	v_pk_mul_f32 v[2:3], v[6:7], v[2:3] op_sel:[1,0] op_sel_hi:[0,1]
	v_lshlrev_b32_e32 v8, 16, v40
	v_pk_fma_f32 v[0:1], v[6:7], v[0:1], v[2:3]
	v_lshlrev_b32_e32 v2, 16, v37
	v_pk_fma_f32 v[0:1], v[4:5], v[8:9], v[0:1] op_sel_hi:[0,1,1]
	v_lshlrev_b32_e32 v8, 16, v33
	v_and_b32_e32 v9, 0xffff0000, v37
	v_and_b32_e32 v3, 0xffff0000, v33
	v_pk_mul_f32 v[8:9], v[6:7], v[8:9] op_sel:[1,0] op_sel_hi:[0,1]
	v_pk_mul_f32 v[0:1], v[0:1], v[10:11]
	v_lshlrev_b32_e32 v10, 16, v41
	v_and_b32_e32 v11, 0xffff0000, v41
	v_pk_fma_f32 v[2:3], v[6:7], v[2:3], v[8:9]
	v_lshlrev_b32_e32 v8, 16, v34
	v_pk_fma_f32 v[2:3], v[4:5], v[10:11], v[2:3] op_sel_hi:[0,1,1]
	v_pk_mul_f32 v[2:3], v[2:3], v[12:13]
	v_and_b32_e32 v9, 0xffff0000, v38
	v_cvt_pk_bf16_f32 v0, v0, v1
	v_cvt_pk_bf16_f32 v1, v2, v3
	v_lshlrev_b32_e32 v2, 16, v38
	v_and_b32_e32 v3, 0xffff0000, v34
	v_pk_mul_f32 v[8:9], v[6:7], v[8:9] op_sel:[1,0] op_sel_hi:[0,1]
	v_lshlrev_b32_e32 v10, 16, v42
	v_and_b32_e32 v11, 0xffff0000, v42
	v_pk_fma_f32 v[2:3], v[6:7], v[2:3], v[8:9]
	v_lshlrev_b32_e32 v8, 16, v39
	v_pk_fma_f32 v[2:3], v[4:5], v[10:11], v[2:3] op_sel_hi:[0,1,1]
	v_lshlrev_b32_e32 v10, 16, v35
	v_and_b32_e32 v11, 0xffff0000, v39
	v_and_b32_e32 v9, 0xffff0000, v35
	v_pk_mul_f32 v[10:11], v[6:7], v[10:11] op_sel:[1,0] op_sel_hi:[0,1]
	v_pk_fma_f32 v[6:7], v[6:7], v[8:9], v[10:11]
	v_lshlrev_b32_e32 v8, 16, v43
	v_and_b32_e32 v9, 0xffff0000, v43
	v_lshlrev_b32_e32 v12, 16, v46
	v_and_b32_e32 v13, 0xffff0000, v46
	v_pk_fma_f32 v[4:5], v[4:5], v[8:9], v[6:7] op_sel_hi:[0,1,1]
	v_lshlrev_b32_e32 v6, 16, v47
	v_and_b32_e32 v7, 0xffff0000, v47
	v_pk_mul_f32 v[2:3], v[2:3], v[12:13]
	v_pk_mul_f32 v[4:5], v[4:5], v[6:7]
	v_cvt_pk_bf16_f32 v2, v2, v3
	v_cvt_pk_bf16_f32 v3, v4, v5
	v_add_u32_e32 v4, s12, v92
	v_ashrrev_i32_e32 v5, 31, v4
	v_lshlrev_b64 v[4:5], 10, v[4:5]
	v_lshl_add_u64 v[4:5], v[66:67], 0, v[4:5]
	global_store_dwordx4 v[4:5], v[0:3], off
	v_and_b32_e32 v9, 0xffff0000, v56
	s_waitcnt vmcnt(35)
	v_lshlrev_b32_e32 v10, 16, v60
	v_max3_f32 v2, v97, v98, v99
	v_sub_f32_e32 v0, v97, v2
	v_exp_f32_e32 v1, v0
	v_sub_f32_e32 v0, v98, v2
	v_exp_f32_e32 v0, v0
	v_sub_f32_e32 v2, v99, v2
	v_exp_f32_e32 v3, v2
	v_and_b32_e32 v11, 0xffff0000, v60
	v_add_f32_e32 v2, v1, v0
	v_lshlrev_b32_e32 v12, 16, v61
	v_add_f32_e32 v2, v3, v2
	v_div_scale_f32 v4, s[14:15], v2, v2, 1.0
	v_rcp_f32_e32 v5, v4
	v_and_b32_e32 v13, 0xffff0000, v61
	v_fma_f32 v6, -v4, v5, 1.0
	v_fmac_f32_e32 v5, v6, v5
	v_div_scale_f32 v6, vcc, 1.0, v2, 1.0
	v_mul_f32_e32 v7, v6, v5
	v_fma_f32 v8, -v4, v7, v6
	v_fmac_f32_e32 v7, v8, v5
	v_fma_f32 v4, -v4, v7, v6
	v_div_fmas_f32 v4, v4, v5, v7
	v_div_fixup_f32 v2, v4, v2, 1.0
	v_mul_f32_e32 v4, v3, v2
	v_pk_mul_f32 v[6:7], v[0:1], v[2:3] op_sel_hi:[1,0]
	v_lshlrev_b32_e32 v2, 16, v48
	v_and_b32_e32 v3, 0xffff0000, v52
	v_lshlrev_b32_e32 v0, 16, v52
	v_and_b32_e32 v1, 0xffff0000, v48
	v_pk_mul_f32 v[2:3], v[6:7], v[2:3] op_sel:[1,0] op_sel_hi:[0,1]
	v_lshlrev_b32_e32 v8, 16, v56
	v_pk_fma_f32 v[0:1], v[6:7], v[0:1], v[2:3]
	v_lshlrev_b32_e32 v2, 16, v53
	v_pk_fma_f32 v[0:1], v[4:5], v[8:9], v[0:1] op_sel_hi:[0,1,1]
	v_lshlrev_b32_e32 v8, 16, v49
	v_and_b32_e32 v9, 0xffff0000, v53
	v_and_b32_e32 v3, 0xffff0000, v49
	v_pk_mul_f32 v[8:9], v[6:7], v[8:9] op_sel:[1,0] op_sel_hi:[0,1]
	v_pk_mul_f32 v[0:1], v[0:1], v[10:11]
	v_lshlrev_b32_e32 v10, 16, v57
	v_and_b32_e32 v11, 0xffff0000, v57
	v_pk_fma_f32 v[2:3], v[6:7], v[2:3], v[8:9]
	v_lshlrev_b32_e32 v8, 16, v50
	v_pk_fma_f32 v[2:3], v[4:5], v[10:11], v[2:3] op_sel_hi:[0,1,1]
	v_pk_mul_f32 v[2:3], v[2:3], v[12:13]
	v_and_b32_e32 v9, 0xffff0000, v54
	v_cvt_pk_bf16_f32 v0, v0, v1
	v_cvt_pk_bf16_f32 v1, v2, v3
	v_lshlrev_b32_e32 v2, 16, v54
	v_and_b32_e32 v3, 0xffff0000, v50
	v_pk_mul_f32 v[8:9], v[6:7], v[8:9] op_sel:[1,0] op_sel_hi:[0,1]
	v_lshlrev_b32_e32 v10, 16, v58
	v_and_b32_e32 v11, 0xffff0000, v58
	v_pk_fma_f32 v[2:3], v[6:7], v[2:3], v[8:9]
	v_lshlrev_b32_e32 v8, 16, v55
	v_pk_fma_f32 v[2:3], v[4:5], v[10:11], v[2:3] op_sel_hi:[0,1,1]
	v_lshlrev_b32_e32 v10, 16, v51
	v_and_b32_e32 v11, 0xffff0000, v55
	v_and_b32_e32 v9, 0xffff0000, v51
	v_pk_mul_f32 v[10:11], v[6:7], v[10:11] op_sel:[1,0] op_sel_hi:[0,1]
	v_pk_fma_f32 v[6:7], v[6:7], v[8:9], v[10:11]
	v_lshlrev_b32_e32 v8, 16, v59
	v_and_b32_e32 v9, 0xffff0000, v59
	v_lshlrev_b32_e32 v12, 16, v62
	v_and_b32_e32 v13, 0xffff0000, v62
	v_pk_fma_f32 v[4:5], v[4:5], v[8:9], v[6:7] op_sel_hi:[0,1,1]
	v_lshlrev_b32_e32 v6, 16, v63
	v_and_b32_e32 v7, 0xffff0000, v63
	v_pk_mul_f32 v[2:3], v[2:3], v[12:13]
	v_pk_mul_f32 v[4:5], v[4:5], v[6:7]
	v_cvt_pk_bf16_f32 v2, v2, v3
	v_cvt_pk_bf16_f32 v3, v4, v5
	v_add_u32_e32 v4, s12, v96
	v_ashrrev_i32_e32 v5, 31, v4
	v_lshlrev_b64 v[4:5], 10, v[4:5]
	v_lshl_add_u64 v[4:5], v[66:67], 0, v[4:5]
	global_store_dwordx4 v[4:5], v[0:3], off
	s_waitcnt vmcnt(29)
; #define CMB(f) { const float lo = (w0 * bflo(og[q][0].f) + w1 * bflo(og[q][1].f) + w2 * bflo(og[q][2].f)) * bflo(z.f); const float hi = (w0 * bfhi(og[q][0].f) + w1 * bfhi(og[q][1].f) + w2 * bfhi(og[q][2].f)) * bfhi(z.f); o.f = cvtpk(lo, hi); }
; __device__ __forceinline__ void attnA_unit(LAS unsigned char* lds, const Args& A, int unit) {
;     ...
;         for (int q = 0; q < 4; ++q) {
;             const int e = (it0 + q) * 512 + tid, tl = e >> 3, ch = e & 7, s = c * 1024 + tl;
;             const float M = fmaxf(ls2[q][0], fmaxf(ls2[q][1], ls2[q][2]));
;             float w0 = __builtin_amdgcn_exp2f(ls2[q][0] - M), w1 = __builtin_amdgcn_exp2f(ls2[q][1] - M), w2 = __builtin_amdgcn_exp2f(ls2[q][2] - M);
;             const float wi = 1.0f / (w0 + w1 + w2); w0 *= wi; w1 *= wi; w2 *= wi;
;             const u32x4 z = zv[q]; u32x4 o;
;     ...
;             CMB(x) CMB(y) CMB(z) CMB(w)
;     ...
;             *(u32x4*)(SAZ + (size_t)(b * 8192 + s) * 512 + h * 64 + ch * 8) = o;
	v_max3_f32 v153, v147, v149, v152
	v_sub_f32_e32 v147, v147, v153
	v_exp_f32_e32 v151, v147
	v_sub_f32_e32 v147, v149, v153
	v_exp_f32_e32 v150, v147
	v_sub_f32_e32 v147, v152, v153
	v_exp_f32_e32 v147, v147
	v_add_f32_e32 v149, v151, v150
	v_add_f32_e32 v149, v147, v149
	v_div_scale_f32 v152, s[14:15], v149, v149, 1.0
	v_rcp_f32_e32 v153, v152
	s_waitcnt vmcnt(11)
	v_lshlrev_b32_e32 v158, 16, v108
	v_fma_f32 v154, -v152, v153, 1.0
	v_fmac_f32_e32 v153, v154, v153
	v_div_scale_f32 v154, vcc, 1.0, v149, 1.0
	v_mul_f32_e32 v156, v154, v153
	v_fma_f32 v157, -v152, v156, v154
	v_fmac_f32_e32 v156, v157, v153
	v_fma_f32 v152, -v152, v156, v154
	v_div_fmas_f32 v152, v152, v153, v156
	v_div_fixup_f32 v152, v152, v149, 1.0
	v_pk_mul_f32 v[150:151], v[150:151], v[152:153] op_sel_hi:[1,0]
	v_lshlrev_b32_e32 v156, 16, v100
	v_and_b32_e32 v157, 0xffff0000, v104
	v_mul_f32_e32 v154, v147, v152
	v_lshlrev_b32_e32 v152, 16, v104
	v_and_b32_e32 v153, 0xffff0000, v100
	v_pk_mul_f32 v[156:157], v[150:151], v[156:157] op_sel:[1,0] op_sel_hi:[0,1]
	v_and_b32_e32 v159, 0xffff0000, v108
	v_pk_fma_f32 v[152:153], v[150:151], v[152:153], v[156:157]
	s_waitcnt vmcnt(10)
	v_lshlrev_b32_e32 v238, 16, v112
	v_and_b32_e32 v239, 0xffff0000, v112
	v_pk_fma_f32 v[152:153], v[154:155], v[158:159], v[152:153] op_sel_hi:[0,1,1]
	v_pk_mul_f32 v[152:153], v[152:153], v[238:239]
	v_lshlrev_b32_e32 v104, 16, v101
	v_cvt_pk_bf16_f32 v100, v152, v153
	v_lshlrev_b32_e32 v152, 16, v105
	v_and_b32_e32 v105, 0xffff0000, v105
	v_and_b32_e32 v153, 0xffff0000, v101
	v_pk_mul_f32 v[104:105], v[150:151], v[104:105] op_sel:[1,0] op_sel_hi:[0,1]
	v_lshlrev_b32_e32 v108, 16, v109
	v_and_b32_e32 v109, 0xffff0000, v109
	v_pk_fma_f32 v[104:105], v[150:151], v[152:153], v[104:105]
	v_lshlrev_b32_e32 v112, 16, v113
	v_and_b32_e32 v113, 0xffff0000, v113
	v_pk_fma_f32 v[104:105], v[154:155], v[108:109], v[104:105] op_sel_hi:[0,1,1]
	v_pk_mul_f32 v[104:105], v[104:105], v[112:113]
	v_lshlrev_b32_e32 v108, 16, v102
	v_and_b32_e32 v109, 0xffff0000, v106
	v_cvt_pk_bf16_f32 v101, v104, v105
	v_lshlrev_b32_e32 v104, 16, v106
	v_and_b32_e32 v105, 0xffff0000, v102
	v_pk_mul_f32 v[108:109], v[150:151], v[108:109] op_sel:[1,0] op_sel_hi:[0,1]
	v_lshlrev_b32_e32 v112, 16, v110
	v_and_b32_e32 v113, 0xffff0000, v110
	v_pk_fma_f32 v[104:105], v[150:151], v[104:105], v[108:109]
	v_lshlrev_b32_e32 v152, 16, v114
	v_and_b32_e32 v153, 0xffff0000, v114
	v_pk_fma_f32 v[104:105], v[154:155], v[112:113], v[104:105] op_sel_hi:[0,1,1]
	v_pk_mul_f32 v[104:105], v[104:105], v[152:153]
	v_lshlrev_b32_e32 v106, 16, v103
	v_cvt_pk_bf16_f32 v102, v104, v105
	v_lshlrev_b32_e32 v104, 16, v107
	v_and_b32_e32 v107, 0xffff0000, v107
	v_and_b32_e32 v105, 0xffff0000, v103
	v_pk_mul_f32 v[106:107], v[150:151], v[106:107] op_sel:[1,0] op_sel_hi:[0,1]
	v_pk_fma_f32 v[104:105], v[150:151], v[104:105], v[106:107]
	v_lshlrev_b32_e32 v106, 16, v111
	v_and_b32_e32 v107, 0xffff0000, v111
	v_pk_fma_f32 v[104:105], v[154:155], v[106:107], v[104:105] op_sel_hi:[0,1,1]
	v_lshlrev_b32_e32 v106, 16, v115
	v_and_b32_e32 v107, 0xffff0000, v115
	v_pk_mul_f32 v[104:105], v[104:105], v[106:107]
	v_and_b32_e32 v109, 0xffff0000, v124
	v_cvt_pk_bf16_f32 v103, v104, v105
	v_add_u32_e32 v104, s12, v146
	v_ashrrev_i32_e32 v105, 31, v104
	v_lshlrev_b64 v[104:105], 10, v[104:105]
	v_lshl_add_u64 v[104:105], v[66:67], 0, v[104:105]
	global_store_dwordx4 v[104:105], v[100:103], off
	s_waitcnt vmcnt(9)
	v_lshlrev_b32_e32 v110, 16, v128
	v_and_b32_e32 v111, 0xffff0000, v128
	v_max3_f32 v102, v155, v240, v241
	v_sub_f32_e32 v100, v155, v102
	v_exp_f32_e32 v101, v100
	v_sub_f32_e32 v100, v240, v102
	v_exp_f32_e32 v100, v100
	v_sub_f32_e32 v102, v241, v102
	v_exp_f32_e32 v103, v102
	v_lshlrev_b32_e32 v112, 16, v129
	v_add_f32_e32 v102, v101, v100
	v_and_b32_e32 v113, 0xffff0000, v129
	v_add_f32_e32 v102, v103, v102
	v_div_scale_f32 v104, s[14:15], v102, v102, 1.0
	v_rcp_f32_e32 v105, v104
	s_nop 0
	v_fma_f32 v106, -v104, v105, 1.0
	v_fmac_f32_e32 v105, v106, v105
	v_div_scale_f32 v106, vcc, 1.0, v102, 1.0
	v_mul_f32_e32 v107, v106, v105
	v_fma_f32 v108, -v104, v107, v106
	v_fmac_f32_e32 v107, v108, v105
	v_fma_f32 v104, -v104, v107, v106
	v_div_fmas_f32 v104, v104, v105, v107
	v_div_fixup_f32 v102, v104, v102, 1.0
	v_mul_f32_e32 v104, v103, v102
	v_pk_mul_f32 v[106:107], v[100:101], v[102:103] op_sel_hi:[1,0]
	v_lshlrev_b32_e32 v102, 16, v116
	v_and_b32_e32 v103, 0xffff0000, v120
	v_lshlrev_b32_e32 v100, 16, v120
	v_and_b32_e32 v101, 0xffff0000, v116
	v_pk_mul_f32 v[102:103], v[106:107], v[102:103] op_sel:[1,0] op_sel_hi:[0,1]
	v_lshlrev_b32_e32 v108, 16, v124
	v_pk_fma_f32 v[100:101], v[106:107], v[100:101], v[102:103]
	v_lshlrev_b32_e32 v102, 16, v121
	v_pk_fma_f32 v[100:101], v[104:105], v[108:109], v[100:101] op_sel_hi:[0,1,1]
	v_lshlrev_b32_e32 v108, 16, v117
	v_and_b32_e32 v109, 0xffff0000, v121
	v_and_b32_e32 v103, 0xffff0000, v117
	v_pk_mul_f32 v[108:109], v[106:107], v[108:109] op_sel:[1,0] op_sel_hi:[0,1]
	v_pk_mul_f32 v[100:101], v[100:101], v[110:111]
	v_lshlrev_b32_e32 v110, 16, v125
	v_and_b32_e32 v111, 0xffff0000, v125
	v_pk_fma_f32 v[102:103], v[106:107], v[102:103], v[108:109]
	v_lshlrev_b32_e32 v108, 16, v118
	v_pk_fma_f32 v[102:103], v[104:105], v[110:111], v[102:103] op_sel_hi:[0,1,1]
	v_pk_mul_f32 v[102:103], v[102:103], v[112:113]
	v_and_b32_e32 v109, 0xffff0000, v122
	v_cvt_pk_bf16_f32 v100, v100, v101
	v_cvt_pk_bf16_f32 v101, v102, v103
	v_lshlrev_b32_e32 v102, 16, v122
	v_and_b32_e32 v103, 0xffff0000, v118
	v_pk_mul_f32 v[108:109], v[106:107], v[108:109] op_sel:[1,0] op_sel_hi:[0,1]
	v_lshlrev_b32_e32 v110, 16, v126
	v_and_b32_e32 v111, 0xffff0000, v126
	v_pk_fma_f32 v[102:103], v[106:107], v[102:103], v[108:109]
	v_lshlrev_b32_e32 v108, 16, v123
	v_pk_fma_f32 v[102:103], v[104:105], v[110:111], v[102:103] op_sel_hi:[0,1,1]
	v_lshlrev_b32_e32 v110, 16, v119
	v_and_b32_e32 v111, 0xffff0000, v123
	v_and_b32_e32 v109, 0xffff0000, v119
	v_pk_mul_f32 v[110:111], v[106:107], v[110:111] op_sel:[1,0] op_sel_hi:[0,1]
	v_pk_fma_f32 v[106:107], v[106:107], v[108:109], v[110:111]
	v_lshlrev_b32_e32 v108, 16, v127
	v_and_b32_e32 v109, 0xffff0000, v127
	v_lshlrev_b32_e32 v112, 16, v130
	v_and_b32_e32 v113, 0xffff0000, v130
	v_pk_fma_f32 v[104:105], v[104:105], v[108:109], v[106:107] op_sel_hi:[0,1,1]
	v_lshlrev_b32_e32 v106, 16, v131
	v_and_b32_e32 v107, 0xffff0000, v131
	v_pk_mul_f32 v[102:103], v[102:103], v[112:113]
	v_pk_mul_f32 v[104:105], v[104:105], v[106:107]
	v_cvt_pk_bf16_f32 v102, v102, v103
	v_cvt_pk_bf16_f32 v103, v104, v105
	v_add_u32_e32 v104, s12, v148
	v_ashrrev_i32_e32 v105, 31, v104
	v_lshlrev_b64 v[104:105], 10, v[104:105]
	v_lshl_add_u64 v[104:105], v[66:67], 0, v[104:105]
	global_store_dwordx4 v[104:105], v[100:103], off
	v_and_b32_e32 v109, 0xffff0000, v140
	s_waitcnt vmcnt(8)
; #define CMB(f) { const float lo = (w0 * bflo(og[q][0].f) + w1 * bflo(og[q][1].f) + w2 * bflo(og[q][2].f)) * bflo(z.f); const float hi = (w0 * bfhi(og[q][0].f) + w1 * bfhi(og[q][1].f) + w2 * bfhi(og[q][2].f)) * bfhi(z.f); o.f = cvtpk(lo, hi); }
; __device__ __forceinline__ void attnA_unit(LAS unsigned char* lds, const Args& A, int unit) {
;     ...
;         for (int q = 0; q < 4; ++q) {
;             const int e = (it0 + q) * 512 + tid, tl = e >> 3, ch = e & 7, s = c * 1024 + tl;
;             const float M = fmaxf(ls2[q][0], fmaxf(ls2[q][1], ls2[q][2]));
;             float w0 = __builtin_amdgcn_exp2f(ls2[q][0] - M), w1 = __builtin_amdgcn_exp2f(ls2[q][1] - M), w2 = __builtin_amdgcn_exp2f(ls2[q][2] - M);
;             const float wi = 1.0f / (w0 + w1 + w2); w0 *= wi; w1 *= wi; w2 *= wi;
;             const u32x4 z = zv[q]; u32x4 o;
;     ...
;             CMB(x) CMB(y) CMB(z) CMB(w)
;     ...
;             *(u32x4*)(SAZ + (size_t)(b * 8192 + s) * 512 + h * 64 + ch * 8) = o;
;         }
;     }
	v_lshlrev_b32_e32 v110, 16, v190
	v_max3_f32 v102, v243, v244, v245
	v_sub_f32_e32 v100, v243, v102
	v_exp_f32_e32 v101, v100
	v_sub_f32_e32 v100, v244, v102
	v_exp_f32_e32 v100, v100
	v_sub_f32_e32 v102, v245, v102
	v_exp_f32_e32 v103, v102
	v_and_b32_e32 v111, 0xffff0000, v190
	v_add_f32_e32 v102, v101, v100
	v_lshlrev_b32_e32 v112, 16, v191
	v_add_f32_e32 v102, v103, v102
	v_div_scale_f32 v104, s[14:15], v102, v102, 1.0
	v_rcp_f32_e32 v105, v104
	v_and_b32_e32 v113, 0xffff0000, v191
	v_fma_f32 v106, -v104, v105, 1.0
	v_fmac_f32_e32 v105, v106, v105
	v_div_scale_f32 v106, vcc, 1.0, v102, 1.0
	v_mul_f32_e32 v107, v106, v105
	v_fma_f32 v108, -v104, v107, v106
	v_fmac_f32_e32 v107, v108, v105
	v_fma_f32 v104, -v104, v107, v106
	v_div_fmas_f32 v104, v104, v105, v107
	v_div_fixup_f32 v102, v104, v102, 1.0
	v_mul_f32_e32 v104, v103, v102
	v_pk_mul_f32 v[106:107], v[100:101], v[102:103] op_sel_hi:[1,0]
	v_lshlrev_b32_e32 v102, 16, v132
	v_and_b32_e32 v103, 0xffff0000, v136
	v_lshlrev_b32_e32 v100, 16, v136
	v_and_b32_e32 v101, 0xffff0000, v132
	v_pk_mul_f32 v[102:103], v[106:107], v[102:103] op_sel:[1,0] op_sel_hi:[0,1]
	v_lshlrev_b32_e32 v108, 16, v140
	v_pk_fma_f32 v[100:101], v[106:107], v[100:101], v[102:103]
	v_lshlrev_b32_e32 v102, 16, v137
	v_pk_fma_f32 v[100:101], v[104:105], v[108:109], v[100:101] op_sel_hi:[0,1,1]
	v_lshlrev_b32_e32 v108, 16, v133
	v_and_b32_e32 v109, 0xffff0000, v137
	v_and_b32_e32 v103, 0xffff0000, v133
	v_pk_mul_f32 v[108:109], v[106:107], v[108:109] op_sel:[1,0] op_sel_hi:[0,1]
	v_pk_mul_f32 v[100:101], v[100:101], v[110:111]
	v_lshlrev_b32_e32 v110, 16, v141
	v_and_b32_e32 v111, 0xffff0000, v141
	v_pk_fma_f32 v[102:103], v[106:107], v[102:103], v[108:109]
	v_lshlrev_b32_e32 v108, 16, v134
	v_pk_fma_f32 v[102:103], v[104:105], v[110:111], v[102:103] op_sel_hi:[0,1,1]
	v_pk_mul_f32 v[102:103], v[102:103], v[112:113]
	v_and_b32_e32 v109, 0xffff0000, v138
	v_cvt_pk_bf16_f32 v100, v100, v101
	v_cvt_pk_bf16_f32 v101, v102, v103
	v_lshlrev_b32_e32 v102, 16, v138
	v_and_b32_e32 v103, 0xffff0000, v134
	v_pk_mul_f32 v[108:109], v[106:107], v[108:109] op_sel:[1,0] op_sel_hi:[0,1]
	v_lshlrev_b32_e32 v110, 16, v142
	v_and_b32_e32 v111, 0xffff0000, v142
	v_pk_fma_f32 v[102:103], v[106:107], v[102:103], v[108:109]
	v_lshlrev_b32_e32 v108, 16, v139
	v_pk_fma_f32 v[102:103], v[104:105], v[110:111], v[102:103] op_sel_hi:[0,1,1]
	v_lshlrev_b32_e32 v110, 16, v135
	v_and_b32_e32 v111, 0xffff0000, v139
	v_and_b32_e32 v109, 0xffff0000, v135
	v_pk_mul_f32 v[110:111], v[106:107], v[110:111] op_sel:[1,0] op_sel_hi:[0,1]
	v_pk_fma_f32 v[106:107], v[106:107], v[108:109], v[110:111]
	v_lshlrev_b32_e32 v108, 16, v143
	v_and_b32_e32 v109, 0xffff0000, v143
	v_lshlrev_b32_e32 v112, 16, v192
	v_and_b32_e32 v113, 0xffff0000, v192
	v_pk_fma_f32 v[104:105], v[104:105], v[108:109], v[106:107] op_sel_hi:[0,1,1]
	v_lshlrev_b32_e32 v106, 16, v193
	v_and_b32_e32 v107, 0xffff0000, v193
	v_pk_mul_f32 v[102:103], v[102:103], v[112:113]
	v_pk_mul_f32 v[104:105], v[104:105], v[106:107]
	v_cvt_pk_bf16_f32 v102, v102, v103
	v_cvt_pk_bf16_f32 v103, v104, v105
	v_add_u32_e32 v104, s12, v242
	v_ashrrev_i32_e32 v105, 31, v104
	v_lshlrev_b64 v[104:105], 10, v[104:105]
	v_lshl_add_u64 v[104:105], v[66:67], 0, v[104:105]
	global_store_dwordx4 v[104:105], v[100:103], off
	v_and_b32_e32 v109, 0xffff0000, v202
	s_waitcnt vmcnt(7)
	v_lshlrev_b32_e32 v110, 16, v206
	v_max3_f32 v102, v247, v248, v249
	v_sub_f32_e32 v100, v247, v102
	v_exp_f32_e32 v101, v100
	v_sub_f32_e32 v100, v248, v102
	v_exp_f32_e32 v100, v100
	v_sub_f32_e32 v102, v249, v102
	v_exp_f32_e32 v103, v102
	v_and_b32_e32 v111, 0xffff0000, v206
	v_add_f32_e32 v102, v101, v100
	v_lshlrev_b32_e32 v112, 16, v207
	v_add_f32_e32 v102, v103, v102
	v_div_scale_f32 v104, s[14:15], v102, v102, 1.0
	v_rcp_f32_e32 v105, v104
	v_and_b32_e32 v113, 0xffff0000, v207
	v_fma_f32 v106, -v104, v105, 1.0
	v_fmac_f32_e32 v105, v106, v105
	v_div_scale_f32 v106, vcc, 1.0, v102, 1.0
	v_mul_f32_e32 v107, v106, v105
	v_fma_f32 v108, -v104, v107, v106
	v_fmac_f32_e32 v107, v108, v105
	v_fma_f32 v104, -v104, v107, v106
	v_div_fmas_f32 v104, v104, v105, v107
	v_div_fixup_f32 v102, v104, v102, 1.0
	v_mul_f32_e32 v104, v103, v102
	v_pk_mul_f32 v[106:107], v[100:101], v[102:103] op_sel_hi:[1,0]
	v_lshlrev_b32_e32 v102, 16, v194
	v_and_b32_e32 v103, 0xffff0000, v198
	v_lshlrev_b32_e32 v100, 16, v198
	v_and_b32_e32 v101, 0xffff0000, v194
	v_pk_mul_f32 v[102:103], v[106:107], v[102:103] op_sel:[1,0] op_sel_hi:[0,1]
	v_lshlrev_b32_e32 v108, 16, v202
	v_pk_fma_f32 v[100:101], v[106:107], v[100:101], v[102:103]
	v_lshlrev_b32_e32 v102, 16, v199
	v_pk_fma_f32 v[100:101], v[104:105], v[108:109], v[100:101] op_sel_hi:[0,1,1]
	v_lshlrev_b32_e32 v108, 16, v195
	v_and_b32_e32 v109, 0xffff0000, v199
	v_and_b32_e32 v103, 0xffff0000, v195
	v_pk_mul_f32 v[108:109], v[106:107], v[108:109] op_sel:[1,0] op_sel_hi:[0,1]
	v_pk_mul_f32 v[100:101], v[100:101], v[110:111]
	v_lshlrev_b32_e32 v110, 16, v203
	v_and_b32_e32 v111, 0xffff0000, v203
	v_pk_fma_f32 v[102:103], v[106:107], v[102:103], v[108:109]
	v_lshlrev_b32_e32 v108, 16, v196
	v_pk_fma_f32 v[102:103], v[104:105], v[110:111], v[102:103] op_sel_hi:[0,1,1]
	v_pk_mul_f32 v[102:103], v[102:103], v[112:113]
	v_and_b32_e32 v109, 0xffff0000, v200
	v_cvt_pk_bf16_f32 v100, v100, v101
	v_cvt_pk_bf16_f32 v101, v102, v103
	v_lshlrev_b32_e32 v102, 16, v200
	v_and_b32_e32 v103, 0xffff0000, v196
	v_pk_mul_f32 v[108:109], v[106:107], v[108:109] op_sel:[1,0] op_sel_hi:[0,1]
	v_lshlrev_b32_e32 v110, 16, v204
	v_and_b32_e32 v111, 0xffff0000, v204
	v_pk_fma_f32 v[102:103], v[106:107], v[102:103], v[108:109]
	v_lshlrev_b32_e32 v108, 16, v201
	v_pk_fma_f32 v[102:103], v[104:105], v[110:111], v[102:103] op_sel_hi:[0,1,1]
	v_lshlrev_b32_e32 v110, 16, v197
	v_and_b32_e32 v111, 0xffff0000, v201
	v_and_b32_e32 v109, 0xffff0000, v197
	v_pk_mul_f32 v[110:111], v[106:107], v[110:111] op_sel:[1,0] op_sel_hi:[0,1]
	v_pk_fma_f32 v[106:107], v[106:107], v[108:109], v[110:111]
	v_lshlrev_b32_e32 v108, 16, v205
	v_and_b32_e32 v109, 0xffff0000, v205
	v_lshlrev_b32_e32 v112, 16, v208
	v_and_b32_e32 v113, 0xffff0000, v208
	v_pk_fma_f32 v[104:105], v[104:105], v[108:109], v[106:107] op_sel_hi:[0,1,1]
	v_lshlrev_b32_e32 v106, 16, v209
	v_and_b32_e32 v107, 0xffff0000, v209
	v_pk_mul_f32 v[102:103], v[102:103], v[112:113]
	v_pk_mul_f32 v[104:105], v[104:105], v[106:107]
	v_cvt_pk_bf16_f32 v102, v102, v103
	v_cvt_pk_bf16_f32 v103, v104, v105
	v_add_u32_e32 v104, s12, v246
	v_ashrrev_i32_e32 v105, 31, v104
	v_lshlrev_b64 v[104:105], 10, v[104:105]
	v_lshl_add_u64 v[104:105], v[66:67], 0, v[104:105]
	global_store_dwordx4 v[104:105], v[100:103], off
	s_movk_i32 s96, 0xc0
	s_mov_b32 s97, 0x8000
